# row phases P5 and P8: loop-invariant gain vectors hoisted out of the row loops (VGPR / per-wave LDS), conservative top-of-loop vmcnt waits replaced by one counted wait at the latch so next-row prefetc
# speedup vs baseline: 1.0212x; 1.0212x over previous
; __device__ __forceinline__ void row_load(f32x4 (&v)[2][4], v2u (&w)[2][4], v2u (&w2)[2][4], const bf16* m1, const bf16* m2, const float* xin, int row, int NGW, int lane) {
;     const int row2 = (row + NGW) < TOK ? row + NGW : row;
;     const f32x4* xr0 = (const f32x4*)(xin + (size_t)row * DM) + lane; const f32x4* xr1 = (const f32x4*)(xin + (size_t)row2 * DM) + lane;
; #pragma unroll
;     for (int j = 0; j < 4; ++j) { v[0][j] = __builtin_nontemporal_load(xr0 + 64 * j); v[1][j] = __builtin_nontemporal_load(xr1 + 64 * j); }
;     if (m1) { const v2u* mr0 = (const v2u*)(m1 + (size_t)row * DM) + lane; const v2u* mr1 = (const v2u*)(m1 + (size_t)row2 * DM) + lane;
; #pragma unroll
;         for (int j = 0; j < 4; ++j) { w[0][j] = __builtin_nontemporal_load(mr0 + 64 * j); w[1][j] = __builtin_nontemporal_load(mr1 + 64 * j); } }
;     if (m2) { const v2u* mr0 = (const v2u*)(m2 + (size_t)row * DM) + lane; const v2u* mr1 = (const v2u*)(m2 + (size_t)row2 * DM) + lane;
; #pragma unroll
;         for (int j = 0; j < 4; ++j) { w2[0][j] = __builtin_nontemporal_load(mr0 + 64 * j); w2[1][j] = __builtin_nontemporal_load(mr1 + 64 * j); } }
; }
; __device__ __forceinline__ void row_add_norm(f32x4 (&v)[2][4], const v2u (&w)[2][4], const float* g, int lane) {
;     f32x4 m0[4], m1[4]; float s0 = 0.f, s1 = 0.f;
; #pragma unroll
;     for (int j = 0; j < 4; ++j) { m0[j] = (f32x4){pg8::bf_lo(w[0][j].x), pg8::bf_hi(w[0][j].x), pg8::bf_lo(w[0][j].y), pg8::bf_hi(w[0][j].y)}; m1[j] = (f32x4){pg8::bf_lo(w[1][j].x), pg8::bf_hi(w[1][j].x), pg8::bf_lo(w[1][j].y), pg8::bf_hi(w[1][j].y)};
;         s0 += (m0[j][0] * m0[j][0] + m0[j][1] * m0[j][1]) + (m0[j][2] * m0[j][2] + m0[j][3] * m0[j][3]); s1 += (m1[j][0] * m1[j][0] + m1[j][1] * m1[j][1]) + (m1[j][2] * m1[j][2] + m1[j][3] * m1[j][3]); }
;     const float r0 = 1.0f / sqrtf(wave_sum(s0) * (1.0f / DM) + 1e-6f), r1 = 1.0f / sqrtf(wave_sum(s1) * (1.0f / DM) + 1e-6f);
; #pragma unroll
;     for (int j = 0; j < 4; ++j) { const f32x4 gg = ((const f32x4*)g)[64 * j + lane]; v[0][j] = v[0][j] + m0[j] * r0 * gg; v[1][j] = v[1][j] + m1[j] * r1 * gg; }
; }
; __device__ __forceinline__ void row_phase(const bf16* m1, const float* g1, const bf16* m2, const float* g2, const float* xin, float* xout, const float* gpre, bf16* hout, int gw, int NGW, int lane_in) {
;     int lane = lane_in; asm volatile("" : "+v"(lane));
.LBB0_697:
	s_or_b64 exec, exec, s[16:17]
	v_readlane_b32 s1, v255, 20
	s_lshl_b32 s24, s1, 10
	s_cmp_eq_u32 s1, 0
	s_cselect_b64 s[8:9], -1, 0
	v_writelane_b32 v255, s8, 37
	s_waitcnt lgkmcnt(0)
	v_mov_b32_e32 v0, v219
	v_writelane_b32 v255, s9, 38
	v_readlane_b32 s8, v254, 8
	v_readlane_b32 s9, v254, 9
	s_andn2_b64 vcc, exec, s[8:9]
	s_barrier
	v_cndmask_b32_e64 v1, 0, 1, s[8:9]
	v_cmp_ne_u32_e64 s[10:11], 1, v1
	s_mov_b32 s0, 0
	s_nop 1
	v_writelane_b32 v255, s10, 39
	s_nop 1
	v_writelane_b32 v255, s11, 40
	s_cbranch_vccnz .LBB0_710
	s_ashr_i32 s1, s0, 31
	v_readlane_b32 s8, v254, 0
	v_readlane_b32 s9, v254, 1
	s_add_u32 s0, s8, s0
	s_addc_u32 s1, s9, s1
	v_readlane_b32 s8, v255, 37
	v_readlane_b32 s9, v255, 38
	s_and_b64 s[8:9], s[8:9], exec
	s_cselect_b32 s3, 0, 0x68
	s_add_u32 s8, s0, s3
	s_addc_u32 s9, s1, 0
	s_load_dwordx2 s[10:11], s[0:1], 0x58
	s_load_dwordx2 s[12:13], s[0:1], 0x70
	s_nop 0
	s_load_dwordx2 s[8:9], s[8:9], 0x0
	s_nop 0
	s_load_dwordx2 s[0:1], s[0:1], 0x40
	s_lshl_b64 s[16:17], s[24:25], 2
	s_waitcnt lgkmcnt(0)
	s_add_u32 s10, s10, s16
	s_addc_u32 s11, s11, s17
	v_readlane_b32 s14, v254, 58
	s_add_u32 s0, s0, s16
	s_addc_u32 s1, s1, s17
	s_add_u32 s16, s12, 0x10000000
	v_readlane_b32 s15, v254, 59
	s_addc_u32 s17, s13, 0
	s_lshl_b64 s[20:21], s[14:15], 2
	s_add_u32 s20, s8, s20
	v_ashrrev_i32_e32 v1, 31, v0
	v_readlane_b32 s22, v254, 60
	s_addc_u32 s21, s9, s21
	v_lshlrev_b64 v[2:3], 4, v[0:1]
	v_readlane_b32 s23, v254, 61
	v_lshl_add_u64 v[4:5], s[20:21], 0, v[2:3]
	s_lshl_b64 s[20:21], s[22:23], 2
	s_add_u32 s20, s8, s20
	s_addc_u32 s21, s9, s21
	v_lshl_add_u64 v[6:7], s[20:21], 0, v[2:3]
	s_lshl_b64 s[20:21], s[14:15], 1
	s_add_u32 s20, s16, s20
	s_addc_u32 s21, s17, s21
	v_lshlrev_b64 v[0:1], 3, v[0:1]
	global_load_dwordx4 v[56:59], v[4:5], off nt
	global_load_dwordx4 v[48:51], v[4:5], off offset:1024 nt
	global_load_dwordx4 v[60:63], v[6:7], off nt
	global_load_dwordx4 v[52:55], v[6:7], off offset:1024 nt
	global_load_dwordx4 v[40:43], v[4:5], off offset:2048 nt
	global_load_dwordx4 v[36:39], v[4:5], off offset:3072 nt
	global_load_dwordx4 v[44:47], v[6:7], off offset:2048 nt
	global_load_dwordx4 v[32:35], v[6:7], off offset:3072 nt
	v_lshl_add_u64 v[4:5], s[20:21], 0, v[0:1]
	s_lshl_b64 s[20:21], s[22:23], 1
	s_add_u32 s20, s16, s20
	s_addc_u32 s21, s17, s21
	v_lshl_add_u64 v[6:7], s[20:21], 0, v[0:1]
	global_load_dwordx2 v[92:93], v[4:5], off nt
	global_load_dwordx2 v[104:105], v[4:5], off offset:512 nt
	global_load_dwordx2 v[94:95], v[4:5], off offset:1024 nt
	global_load_dwordx2 v[100:101], v[4:5], off offset:1536 nt
	global_load_dwordx2 v[106:107], v[6:7], off nt
	global_load_dwordx2 v[96:97], v[6:7], off offset:512 nt
	global_load_dwordx2 v[102:103], v[6:7], off offset:1024 nt
	global_load_dwordx2 v[98:99], v[6:7], off offset:1536 nt
	v_lshl_add_u64 v[66:67], s[16:17], 0, v[0:1]
	v_lshl_add_u64 v[68:69], s[0:1], 0, v[2:3]
	v_lshl_add_u64 v[0:1], s[12:13], 0, v[0:1]
	s_mov_b64 s[0:1], 0x18000000
	v_lshl_add_u64 v[64:65], s[8:9], 0, v[2:3]
	v_lshl_add_u64 v[70:71], v[0:1], 0, s[0:1]
	v_lshl_add_u64 v[72:73], s[10:11], 0, v[2:3]
	v_readlane_b32 s22, v254, 56
	v_readlane_b32 s23, v254, 57
	global_load_dwordx4 v[144:147], v[68:69], off
	global_load_dwordx4 v[148:151], v[68:69], off offset:1024
	global_load_dwordx4 v[152:155], v[68:69], off offset:2048
	global_load_dwordx4 v[156:159], v[68:69], off offset:3072
	global_load_dwordx4 v[160:163], v[72:73], off
	global_load_dwordx4 v[164:167], v[72:73], off offset:1024
	global_load_dwordx4 v[168:171], v[72:73], off offset:2048
	global_load_dwordx4 v[172:175], v[72:73], off offset:3072
	s_waitcnt vmcnt(0)
	s_branch .LBB0_700
.LBB0_699:
	s_waitcnt vmcnt(4)
	s_add_i32 s22, s0, s33
	v_mov_b64_e32 v[34:35], v[18:19]
	s_cmp_lt_i32 s22, 0x8000
	v_mov_b64_e32 v[98:99], v[80:81]
	v_mov_b64_e32 v[102:103], v[82:83]
	v_mov_b64_e32 v[96:97], v[84:85]
	v_mov_b64_e32 v[106:107], v[86:87]
	v_mov_b64_e32 v[100:101], v[88:89]
	v_mov_b64_e32 v[94:95], v[78:79]
	v_mov_b64_e32 v[104:105], v[76:77]
	v_mov_b64_e32 v[92:93], v[74:75]
	v_mov_b64_e32 v[32:33], v[16:17]
	v_mov_b32_e32 v56, v8
	v_mov_b32_e32 v57, v9
	v_mov_b32_e32 v58, v10
	v_mov_b32_e32 v59, v11
	v_mov_b32_e32 v48, v12
	v_mov_b32_e32 v49, v13
	v_mov_b32_e32 v50, v14
	v_mov_b32_e32 v51, v15
	v_mov_b32_e32 v40, v24
	v_mov_b32_e32 v41, v25
	v_mov_b32_e32 v42, v26
	v_mov_b32_e32 v43, v27
	v_mov_b32_e32 v36, v28
	v_mov_b32_e32 v37, v29
	v_mov_b32_e32 v38, v30
	v_mov_b32_e32 v39, v31
	v_mov_b32_e32 v60, v4
	v_mov_b32_e32 v61, v5
	v_mov_b32_e32 v62, v6
	v_mov_b32_e32 v63, v7
	v_mov_b32_e32 v52, v0
	v_mov_b32_e32 v53, v1
	v_mov_b32_e32 v54, v2
	v_mov_b32_e32 v55, v3
	v_mov_b32_e32 v44, v20
	v_mov_b32_e32 v45, v21
	v_mov_b32_e32 v46, v22
	v_mov_b32_e32 v47, v23
	s_cbranch_scc0 .LBB0_710

; __device__ __forceinline__ float bf_lo(unsigned w) { return __uint_as_float(w << 16); }
; __device__ __forceinline__ float bf_hi(unsigned w) { return __uint_as_float(w & 0xffff0000u); }
; __device__ __forceinline__ void row_add_norm(f32x4 (&v)[2][4], const v2u (&w)[2][4], const float* g, int lane) {
;     f32x4 m0[4], m1[4]; float s0 = 0.f, s1 = 0.f;
; #pragma unroll
;     for (int j = 0; j < 4; ++j) { m0[j] = (f32x4){pg8::bf_lo(w[0][j].x), pg8::bf_hi(w[0][j].x), pg8::bf_lo(w[0][j].y), pg8::bf_hi(w[0][j].y)}; m1[j] = (f32x4){pg8::bf_lo(w[1][j].x), pg8::bf_hi(w[1][j].x), pg8::bf_lo(w[1][j].y), pg8::bf_hi(w[1][j].y)};
;         s0 += (m0[j][0] * m0[j][0] + m0[j][1] * m0[j][1]) + (m0[j][2] * m0[j][2] + m0[j][3] * m0[j][3]); s1 += (m1[j][0] * m1[j][0] + m1[j][1] * m1[j][1]) + (m1[j][2] * m1[j][2] + m1[j][3] * m1[j][3]); }
;     const float r0 = 1.0f / sqrtf(wave_sum(s0) * (1.0f / DM) + 1e-6f), r1 = 1.0f / sqrtf(wave_sum(s1) * (1.0f / DM) + 1e-6f);
; #pragma unroll
;     for (int j = 0; j < 4; ++j) { const f32x4 gg = ((const f32x4*)g)[64 * j + lane]; v[0][j] = v[0][j] + m0[j] * r0 * gg; v[1][j] = v[1][j] + m1[j] * r1 * gg; }
; }
.LBB0_702:
	v_and_b32_e32 v90, 0xffff0000, v92
	v_lshlrev_b32_e32 v91, 16, v93
	v_and_b32_e32 v121, 0xffff0000, v97
	v_and_b32_e32 v120, 0xffff0000, v96
	v_lshlrev_b32_e32 v92, 16, v92
	v_and_b32_e32 v93, 0xffff0000, v93
	v_pk_mul_f32 v[108:109], v[90:91], v[90:91]
	v_lshlrev_b32_e32 v119, 16, v97
	v_lshlrev_b32_e32 v118, 16, v96
	v_pk_mul_f32 v[96:97], v[120:121], v[120:121]
	v_pk_fma_f32 v[108:109], v[92:93], v[92:93], v[108:109]
	v_and_b32_e32 v114, 0xffff0000, v104
	v_lshlrev_b32_e32 v115, 16, v105
	v_pk_fma_f32 v[96:97], v[118:119], v[118:119], v[96:97]
	v_pk_add_f32 v[126:127], v[108:109], v[108:109] op_sel_hi:[0,1]
	v_lshlrev_b32_e32 v116, 16, v104
	v_and_b32_e32 v117, 0xffff0000, v105
	v_pk_mul_f32 v[104:105], v[114:115], v[114:115]
	v_pk_add_f32 v[132:133], v[96:97], v[96:97] op_sel_hi:[0,1]
	v_lshlrev_b32_e32 v108, 16, v94
	v_and_b32_e32 v109, 0xffff0000, v94
	v_and_b32_e32 v110, 0xffff0000, v95
	v_lshlrev_b32_e32 v96, 16, v100
	v_pk_fma_f32 v[104:105], v[116:117], v[116:117], v[104:105]
	v_mul_f32_e32 v97, v108, v108
	v_mul_f32_e32 v135, v109, v109
	v_lshlrev_b32_e32 v111, 16, v95
	v_mul_f32_e32 v94, v110, v110
	v_mov_b32_e32 v134, v96
	v_pk_add_f32 v[130:131], v[104:105], v[104:105] op_sel_hi:[0,1]
	v_pk_fma_f32 v[136:137], v[110:111], v[110:111], v[94:95] op_sel_hi:[1,1,0]
	v_and_b32_e32 v105, 0xffff0000, v100
	v_lshlrev_b32_e32 v100, 16, v101
	v_and_b32_e32 v101, 0xffff0000, v101
	v_pk_add_f32 v[134:135], v[96:97], v[134:135]
	v_mul_f32_e32 v136, v105, v105
	v_mul_f32_e32 v126, v100, v100
	v_mul_f32_e32 v130, v101, v101
	v_mul_f32_e32 v142, v96, v96
	v_mov_b32_e32 v143, v135
	v_and_b32_e32 v125, 0xffff0000, v107
	v_and_b32_e32 v124, 0xffff0000, v106
	v_pk_add_f32 v[134:135], v[142:143], v[136:137]
	v_pk_add_f32 v[126:127], v[130:131], v[126:127]
	v_lshlrev_b32_e32 v123, 16, v107
	v_lshlrev_b32_e32 v122, 16, v106
	v_pk_mul_f32 v[106:107], v[124:125], v[124:125]
	v_pk_add_f32 v[126:127], v[134:135], v[126:127]
	v_pk_fma_f32 v[106:107], v[122:123], v[122:123], v[106:107]
	v_add_f32_e32 v97, v126, v127
	v_pk_add_f32 v[128:129], v[106:107], v[106:107] op_sel_hi:[0,1]
	v_lshlrev_b32_e32 v106, 16, v102
	v_and_b32_e32 v107, 0xffff0000, v102
	ds_bpermute_b32 v102, v226, v97
	v_lshlrev_b32_e32 v112, 16, v103
	v_mul_f32_e32 v95, v106, v106
	v_and_b32_e32 v113, 0xffff0000, v103
	v_mul_f32_e32 v94, v112, v112
	s_waitcnt lgkmcnt(0)
	v_add_f32_e32 v97, v97, v102
	ds_bpermute_b32 v102, v227, v97
	v_pk_fma_f32 v[140:141], v[112:113], v[112:113], v[94:95] op_sel_hi:[1,1,0]
	v_lshlrev_b32_e32 v94, 16, v98
	v_mul_f32_e32 v139, v107, v107
	v_mov_b32_e32 v138, v94
	s_waitcnt lgkmcnt(0)
	v_add_f32_e32 v97, v97, v102
	ds_bpermute_b32 v102, v228, v97
	v_and_b32_e32 v103, 0xffff0000, v98
	v_lshlrev_b32_e32 v98, 16, v99
	v_and_b32_e32 v99, 0xffff0000, v99
	v_pk_add_f32 v[130:131], v[94:95], v[138:139]
	s_waitcnt lgkmcnt(0)
	v_add_f32_e32 v97, v97, v102
	ds_bpermute_b32 v102, v229, v97
	v_mul_f32_e32 v140, v103, v103
	v_mul_f32_e32 v132, v98, v98
	v_mul_f32_e32 v128, v99, v99
	v_mul_f32_e32 v126, v94, v94
	s_waitcnt lgkmcnt(0)
	v_add_f32_e32 v97, v97, v102
	ds_bpermute_b32 v102, v230, v97
	v_mov_b32_e32 v127, v131
	v_pk_add_f32 v[126:127], v[126:127], v[140:141]
	v_pk_add_f32 v[128:129], v[132:133], v[128:129]
	s_add_i32 s0, s22, s33
	s_waitcnt lgkmcnt(0)
	v_add_f32_e32 v97, v97, v102
	ds_bpermute_b32 v102, v231, v97
	v_pk_add_f32 v[126:127], v[126:127], v[128:129]
	s_cmp_lt_i32 s0, 0x8000
	v_add_f32_e32 v95, v126, v127
	s_cselect_b64 s[16:17], -1, 0
	s_waitcnt lgkmcnt(0)
	v_add_f32_e32 v97, v97, v102
	v_fmamk_f32 v97, v97, 0x3a800000, v223
	v_cmp_gt_f32_e32 vcc, s64, v97
	v_mul_f32_e32 v102, 0x4f800000, v97
	s_and_b64 s[8:9], s[16:17], exec
	v_cndmask_b32_e32 v97, v97, v102, vcc
	v_sqrt_f32_e32 v102, v97
	s_cselect_b32 s8, s0, s22
	s_ashr_i32 s9, s8, 31
	s_lshl_b64 s[48:49], s[8:9], 11
	v_add_u32_e32 v104, -1, v102
	v_fma_f32 v126, -v104, v102, v97
	v_cmp_ge_f32_e64 s[42:43], 0, v126
	v_add_u32_e32 v126, 1, v102
	v_mov_b32_e32 v131, v93
	v_cndmask_b32_e64 v104, v102, v104, s[42:43]
	v_fma_f32 v102, -v126, v102, v97
	v_cmp_lt_f32_e64 s[42:43], 0, v102
	v_mov_b32_e32 v93, v90
	v_mov_b32_e32 v130, v91
	v_cndmask_b32_e64 v102, v104, v126, s[42:43]
	v_mul_f32_e32 v104, 0x37800000, v102
	v_cndmask_b32_e32 v102, v102, v104, vcc
	v_cmp_class_f32_e32 vcc, v97, v222
	s_ashr_i32 s23, s22, 31
	s_lshl_b64 s[22:23], s[22:23], 11
	v_cndmask_b32_e32 v97, v102, v97, vcc
	v_div_scale_f32 v102, s[8:9], v97, v97, 1.0
	v_rcp_f32_e32 v104, v102
	s_cmpk_gt_i32 s0, 0x7fff
	v_fma_f32 v126, -v102, v104, 1.0
	v_fmac_f32_e32 v104, v126, v104
	v_div_scale_f32 v126, vcc, 1.0, v97, 1.0
	v_mul_f32_e32 v127, v126, v104
	v_fma_f32 v128, -v102, v127, v126
	v_fmac_f32_e32 v127, v128, v104
	v_fma_f32 v102, -v102, v127, v126
	v_div_fmas_f32 v102, v102, v104, v127
	v_div_fixup_f32 v102, v102, v97, 1.0
	ds_bpermute_b32 v97, v226, v95
	v_pk_mul_f32 v[90:91], v[102:103], v[92:93] op_sel_hi:[0,1]
	v_pk_mul_f32 v[130:131], v[102:103], v[130:131] op_sel_hi:[0,1]
	s_waitcnt lgkmcnt(0)
	v_add_f32_e32 v95, v95, v97
	ds_bpermute_b32 v97, v227, v95
	s_waitcnt lgkmcnt(0)
	v_add_f32_e32 v95, v95, v97
	ds_bpermute_b32 v97, v228, v95
	s_waitcnt lgkmcnt(0)
	v_add_f32_e32 v95, v95, v97
	ds_bpermute_b32 v97, v229, v95
	s_waitcnt lgkmcnt(0)
	v_add_f32_e32 v95, v95, v97
	ds_bpermute_b32 v97, v230, v95
	s_waitcnt lgkmcnt(0)
	v_add_f32_e32 v95, v95, v97
	ds_bpermute_b32 v97, v231, v95
	s_waitcnt lgkmcnt(0)
; __device__ __forceinline__ void row_add_norm(f32x4 (&v)[2][4], const v2u (&w)[2][4], const float* g, int lane) {
;     ...
;     const float r0 = 1.0f / sqrtf(wave_sum(s0) * (1.0f / DM) + 1e-6f), r1 = 1.0f / sqrtf(wave_sum(s1) * (1.0f / DM) + 1e-6f);
; #pragma unroll
;     for (int j = 0; j < 4; ++j) { const f32x4 gg = ((const f32x4*)g)[64 * j + lane]; v[0][j] = v[0][j] + m0[j] * r0 * gg; v[1][j] = v[1][j] + m1[j] * r1 * gg; }
; }
; __device__ __forceinline__ void row_phase(const bf16* m1, const float* g1, const bf16* m2, const float* g2, const float* xin, float* xout, const float* gpre, bf16* hout, int gw, int NGW, int lane_in) {
;     int lane = lane_in; asm volatile("" : "+v"(lane));
;     f32x4 v[2][4]; v2u w[2][4], w2[2][4];
;     if (gw < TOK) row_load(v, w, w2, m1, m2, xin, gw, NGW, lane);
;     for (int row = gw; row < TOK; row += 2 * NGW) {
;         const bool two = (row + NGW) < TOK; const int row2 = two ? row + NGW : row;
;         f32x4 nv[2][4]; v2u nw[2][4], nw2[2][4];
;         const int nrow = row + 2 * NGW;
;         if (nrow < TOK) row_load(nv, nw, nw2, m1, m2, xin, nrow, NGW, lane);
;         if (m1) row_add_norm(v, w, g1, lane);
;         if (m2) row_add_norm(v, w2, g2, lane);
;         if (xout) { f32x4* xo0 = (f32x4*)(xout + (size_t)row * DM) + lane; f32x4* xo1 = (f32x4*)(xout + (size_t)row2 * DM) + lane;
; #pragma unroll
;             for (int j = 0; j < 4; ++j) { __builtin_nontemporal_store(v[0][j], xo0 + 64 * j); if (two) __builtin_nontemporal_store(v[1][j], xo1 + 64 * j); } }
;         if (hout) {
;             float s0 = 0.f, s1 = 0.f;
; #pragma unroll
;             for (int j = 0; j < 4; ++j) { s0 += (v[0][j][0] * v[0][j][0] + v[0][j][1] * v[0][j][1]) + (v[0][j][2] * v[0][j][2] + v[0][j][3] * v[0][j][3]); s1 += (v[1][j][0] * v[1][j][0] + v[1][j][1] * v[1][j][1]) + (v[1][j][2] * v[1][j][2] + v[1][j][3] * v[1][j][3]); }
;             const float r0 = 1.0f / sqrtf(wave_sum(s0) * (1.0f / DM) + 1e-6f), r1 = 1.0f / sqrtf(wave_sum(s1) * (1.0f / DM) + 1e-6f);
	v_add_f32_e32 v95, v95, v97
	v_fmamk_f32 v95, v95, 0x3a800000, v223
	v_cmp_gt_f32_e32 vcc, s64, v95
	v_mul_f32_e32 v97, 0x4f800000, v95
	s_nop 0
	v_cndmask_b32_e32 v95, v95, v97, vcc
	v_sqrt_f32_e32 v97, v95
	s_nop 0
	v_add_u32_e32 v104, -1, v97
	v_fma_f32 v126, -v104, v97, v95
	v_cmp_ge_f32_e64 s[42:43], 0, v126
	v_add_u32_e32 v126, 1, v97
	s_nop 0
	v_cndmask_b32_e64 v104, v97, v104, s[42:43]
	v_fma_f32 v97, -v126, v97, v95
	v_cmp_lt_f32_e64 s[42:43], 0, v97
	s_nop 1
	v_cndmask_b32_e64 v97, v104, v126, s[42:43]
	v_mul_f32_e32 v104, 0x37800000, v97
	v_cndmask_b32_e32 v97, v97, v104, vcc
	v_cmp_class_f32_e32 vcc, v95, v222
	s_nop 1
	v_cndmask_b32_e32 v95, v97, v95, vcc
	v_div_scale_f32 v97, s[8:9], v95, v95, 1.0
	v_rcp_f32_e32 v104, v97
	s_nop 0
	v_fma_f32 v126, -v97, v104, 1.0
	v_fmac_f32_e32 v104, v126, v104
	v_div_scale_f32 v126, vcc, 1.0, v95, 1.0
	v_mul_f32_e32 v127, v126, v104
	v_fma_f32 v128, -v97, v127, v126
	v_fmac_f32_e32 v127, v128, v104
	v_fma_f32 v97, -v97, v127, v126
	v_div_fmas_f32 v97, v97, v104, v127
	v_mov_b64_e32 v[126:127], v[144:145]
	v_mov_b64_e32 v[128:129], v[146:147]
	v_div_fixup_f32 v104, v97, v95, 1.0
	v_mov_b32_e32 v97, v105
	v_mov_b32_e32 v95, v103
	v_pk_fma_f32 v[90:91], v[126:127], v[90:91], v[56:57]
	v_mov_b32_e32 v56, v122
	v_mov_b32_e32 v57, v124
	v_mov_b32_e32 v124, v123
	v_pk_fma_f32 v[92:93], v[128:129], v[130:131], v[58:59]
	v_pk_mul_f32 v[58:59], v[104:105], v[56:57] op_sel_hi:[0,1]
	v_pk_mul_f32 v[56:57], v[104:105], v[124:125] op_sel_hi:[0,1]
	v_mov_b64_e32 v[122:123], v[148:149]
	v_mov_b64_e32 v[124:125], v[150:151]
	v_pk_fma_f32 v[58:59], v[126:127], v[58:59], v[60:61]
	v_mov_b32_e32 v60, v116
	v_mov_b32_e32 v61, v114
	v_mov_b32_e32 v116, v115
	v_pk_fma_f32 v[56:57], v[128:129], v[56:57], v[62:63]
	v_pk_mul_f32 v[62:63], v[102:103], v[60:61] op_sel_hi:[0,1]
	v_pk_mul_f32 v[60:61], v[102:103], v[116:117] op_sel_hi:[0,1]
	v_mov_b64_e32 v[114:115], v[152:153]
	v_mov_b64_e32 v[116:117], v[154:155]
	v_pk_fma_f32 v[62:63], v[122:123], v[62:63], v[48:49]
	v_mov_b32_e32 v48, v118
	v_mov_b32_e32 v49, v120
	v_mov_b32_e32 v120, v119
	v_pk_fma_f32 v[60:61], v[124:125], v[60:61], v[50:51]
	v_pk_mul_f32 v[50:51], v[104:105], v[48:49] op_sel_hi:[0,1]
	v_pk_mul_f32 v[48:49], v[104:105], v[120:121] op_sel_hi:[0,1]
	v_pk_fma_f32 v[48:49], v[124:125], v[48:49], v[54:55]
	v_pk_fma_f32 v[50:51], v[122:123], v[50:51], v[52:53]
	v_pk_mul_f32 v[54:55], v[108:109], v[102:103] op_sel_hi:[1,0]
	v_pk_mul_f32 v[52:53], v[110:111], v[102:103] op_sel:[1,0] op_sel_hi:[0,0]
	v_pk_fma_f32 v[52:53], v[116:117], v[52:53], v[42:43]
	v_pk_fma_f32 v[54:55], v[114:115], v[54:55], v[40:41]
	v_pk_mul_f32 v[40:41], v[106:107], v[104:105] op_sel_hi:[1,0]
	v_pk_mul_f32 v[42:43], v[112:113], v[104:105] op_sel_hi:[1,0]
	v_pk_fma_f32 v[44:45], v[114:115], v[40:41], v[44:45]
	v_pk_fma_f32 v[46:47], v[116:117], v[42:43], v[46:47]
	v_mov_b64_e32 v[40:41], v[156:157]
	v_mov_b64_e32 v[42:43], v[158:159]
	v_pk_mul_f32 v[106:107], v[96:97], v[102:103] op_sel_hi:[1,0]
	v_pk_mul_f32 v[96:97], v[100:101], v[102:103] op_sel_hi:[1,0]
	v_pk_fma_f32 v[100:101], v[106:107], v[40:41], v[36:37]
	v_pk_fma_f32 v[96:97], v[96:97], v[42:43], v[38:39]
	v_pk_mul_f32 v[38:39], v[94:95], v[104:105] op_sel_hi:[1,0]
	v_pk_mul_f32 v[36:37], v[98:99], v[104:105] op_sel_hi:[1,0]
	v_pk_fma_f32 v[38:39], v[40:41], v[38:39], v[32:33]
	v_pk_fma_f32 v[36:37], v[42:43], v[36:37], v[34:35]
	v_pk_mul_f32 v[32:33], v[92:93], v[92:93]
	v_pk_mul_f32 v[34:35], v[90:91], v[90:91]
	s_nop 0
	v_pk_mov_b32 v[40:41], v[34:35], v[32:33] op_sel:[1,0]
	v_mov_b32_e32 v35, v33
	v_pk_add_f32 v[32:33], v[40:41], v[34:35]
	v_pk_mul_f32 v[34:35], v[56:57], v[56:57]
	v_pk_mul_f32 v[40:41], v[58:59], v[58:59]
	v_pk_add_f32 v[32:33], v[32:33], v[32:33] op_sel_hi:[0,1]
	v_pk_mov_b32 v[42:43], v[40:41], v[34:35] op_sel:[1,0]
	v_mov_b32_e32 v41, v35
	v_pk_add_f32 v[34:35], v[42:43], v[40:41]
	v_pk_mul_f32 v[40:41], v[60:61], v[60:61]
	v_pk_mul_f32 v[42:43], v[62:63], v[62:63]
	v_mul_f32_e32 v32, v54, v54
	v_pk_mov_b32 v[94:95], v[42:43], v[40:41] op_sel:[1,0]
	v_mov_b32_e32 v43, v41
	v_pk_add_f32 v[40:41], v[94:95], v[42:43]
	v_pk_mul_f32 v[42:43], v[48:49], v[48:49]
	v_pk_mul_f32 v[94:95], v[50:51], v[50:51]
	v_pk_add_f32 v[40:41], v[40:41], v[40:41] op_sel_hi:[0,1]
	v_pk_mov_b32 v[98:99], v[94:95], v[42:43] op_sel:[1,0]
	v_mov_b32_e32 v95, v43
	v_pk_add_f32 v[42:43], v[98:99], v[94:95]
	v_pk_fma_f32 v[94:95], v[54:55], v[54:55], v[32:33] op_sel_hi:[1,1,0]
	v_mul_f32_e32 v32, v52, v52
	v_pk_fma_f32 v[98:99], v[52:53], v[52:53], v[32:33] op_sel_hi:[1,1,0]
	v_mul_f32_e32 v32, v44, v44
	v_pk_fma_f32 v[102:103], v[44:45], v[44:45], v[32:33] op_sel_hi:[1,1,0]
	v_mul_f32_e32 v32, v46, v46
	v_pk_fma_f32 v[104:105], v[46:47], v[46:47], v[32:33] op_sel_hi:[1,1,0]
	v_mul_f32_e32 v94, v100, v100
	v_mul_f32_e32 v98, v101, v101
	v_mul_f32_e32 v32, v96, v96
	v_mul_f32_e32 v40, v97, v97
	v_pk_add_f32 v[34:35], v[34:35], v[34:35] op_sel_hi:[0,1]
	v_pk_add_f32 v[42:43], v[42:43], v[42:43] op_sel_hi:[0,1]
	v_pk_add_f32 v[94:95], v[94:95], v[98:99]
	v_pk_add_f32 v[32:33], v[32:33], v[40:41]
	v_mul_f32_e32 v102, v38, v38
	v_pk_add_f32 v[32:33], v[94:95], v[32:33]
	v_mul_f32_e32 v104, v39, v39
	v_mul_f32_e32 v34, v36, v36
	v_mul_f32_e32 v42, v37, v37
	v_add_f32_e32 v40, v32, v33
	v_pk_add_f32 v[32:33], v[102:103], v[104:105]
	v_pk_add_f32 v[34:35], v[34:35], v[42:43]
	v_lshl_add_u64 v[98:99], v[70:71], 0, s[22:23]
	v_pk_add_f32 v[32:33], v[32:33], v[34:35]
	s_nop 0
	v_add_f32_e32 v32, v32, v33
	ds_bpermute_b32 v33, v226, v40
	s_waitcnt lgkmcnt(0)
	v_add_f32_e32 v33, v40, v33
	ds_bpermute_b32 v34, v227, v33
	s_waitcnt lgkmcnt(0)
; __device__ __forceinline__ unsigned pk2(float lo, float hi) { return pg8::cvt_pk_bf16(lo, hi); }
; __device__ __forceinline__ void row_phase(const bf16* m1, const float* g1, const bf16* m2, const float* g2, const float* xin, float* xout, const float* gpre, bf16* hout, int gw, int NGW, int lane_in) {
;     ...
;             const float r0 = 1.0f / sqrtf(wave_sum(s0) * (1.0f / DM) + 1e-6f), r1 = 1.0f / sqrtf(wave_sum(s1) * (1.0f / DM) + 1e-6f);
;             v2u* ho0 = (v2u*)(hout + (size_t)row * DM) + lane; v2u* ho1 = (v2u*)(hout + (size_t)row2 * DM) + lane;
; #pragma unroll
;             for (int j = 0; j < 4; ++j) { const f32x4 g = ((const f32x4*)gpre)[64 * j + lane]; const f32x4 y0 = v[0][j] * r0 * g, y1 = v[1][j] * r1 * g;
;                 v2u a0, a1; a0.x = pk2(y0[0], y0[1]); a0.y = pk2(y0[2], y0[3]); a1.x = pk2(y1[0], y1[1]); a1.y = pk2(y1[2], y1[3]); ho0[64 * j] = a0; if (two) ho1[64 * j] = a1; }
;         }
; #pragma unroll
;         for (int j = 0; j < 4; ++j) { v[0][j] = nv[0][j]; v[1][j] = nv[1][j]; w[0][j] = nw[0][j]; w[1][j] = nw[1][j]; w2[0][j] = nw2[0][j]; w2[1][j] = nw2[1][j]; }
;     }
	v_add_f32_e32 v33, v33, v34
	ds_bpermute_b32 v34, v228, v33
	s_waitcnt lgkmcnt(0)
	v_add_f32_e32 v33, v33, v34
	ds_bpermute_b32 v34, v229, v33
	s_waitcnt lgkmcnt(0)
	v_add_f32_e32 v33, v33, v34
	ds_bpermute_b32 v34, v230, v33
	s_waitcnt lgkmcnt(0)
	v_add_f32_e32 v33, v33, v34
	ds_bpermute_b32 v34, v231, v33
	s_waitcnt lgkmcnt(0)
	v_add_f32_e32 v33, v33, v34
	v_fmamk_f32 v33, v33, 0x3a800000, v223
	v_cmp_gt_f32_e32 vcc, s64, v33
	v_mul_f32_e32 v34, 0x4f800000, v33
	s_nop 0
	v_cndmask_b32_e32 v33, v33, v34, vcc
	v_sqrt_f32_e32 v34, v33
	s_nop 0
	v_add_u32_e32 v35, -1, v34
	v_fma_f32 v40, -v35, v34, v33
	v_cmp_ge_f32_e64 s[42:43], 0, v40
	v_add_u32_e32 v40, 1, v34
	s_nop 0
	v_cndmask_b32_e64 v35, v34, v35, s[42:43]
	v_fma_f32 v34, -v40, v34, v33
	v_cmp_lt_f32_e64 s[42:43], 0, v34
	s_nop 1
	v_cndmask_b32_e64 v34, v35, v40, s[42:43]
	v_mul_f32_e32 v35, 0x37800000, v34
	v_cndmask_b32_e32 v34, v34, v35, vcc
	v_cmp_class_f32_e32 vcc, v33, v222
	s_nop 1
	v_cndmask_b32_e32 v33, v34, v33, vcc
	v_div_scale_f32 v34, s[8:9], v33, v33, 1.0
	v_rcp_f32_e32 v35, v34
	s_nop 0
	v_fma_f32 v40, -v34, v35, 1.0
	v_fmac_f32_e32 v35, v40, v35
	v_div_scale_f32 v40, vcc, 1.0, v33, 1.0
	v_mul_f32_e32 v41, v40, v35
	v_fma_f32 v42, -v34, v41, v40
	v_fmac_f32_e32 v41, v42, v35
	v_fma_f32 v34, -v34, v41, v40
	v_div_fmas_f32 v34, v34, v35, v41
	v_div_fixup_f32 v40, v34, v33, 1.0
	ds_bpermute_b32 v33, v226, v32
	s_waitcnt lgkmcnt(0)
	v_add_f32_e32 v32, v32, v33
	ds_bpermute_b32 v33, v227, v32
	s_waitcnt lgkmcnt(0)
	v_add_f32_e32 v32, v32, v33
	ds_bpermute_b32 v33, v228, v32
	s_waitcnt lgkmcnt(0)
	v_add_f32_e32 v32, v32, v33
	ds_bpermute_b32 v33, v229, v32
	s_waitcnt lgkmcnt(0)
	v_add_f32_e32 v32, v32, v33
	ds_bpermute_b32 v33, v230, v32
	s_waitcnt lgkmcnt(0)
	v_add_f32_e32 v32, v32, v33
	ds_bpermute_b32 v33, v231, v32
	s_waitcnt lgkmcnt(0)
	v_add_f32_e32 v32, v32, v33
	v_fmamk_f32 v32, v32, 0x3a800000, v223
	v_cmp_gt_f32_e32 vcc, s64, v32
	v_mul_f32_e32 v33, 0x4f800000, v32
	s_nop 0
	v_cndmask_b32_e32 v32, v32, v33, vcc
	v_sqrt_f32_e32 v33, v32
	s_nop 0
	v_add_u32_e32 v34, -1, v33
	v_fma_f32 v35, -v34, v33, v32
	v_cmp_ge_f32_e64 s[42:43], 0, v35
	v_add_u32_e32 v35, 1, v33
	s_nop 0
	v_cndmask_b32_e64 v34, v33, v34, s[42:43]
	v_fma_f32 v33, -v35, v33, v32
	v_cmp_lt_f32_e64 s[42:43], 0, v33
	s_nop 1
	v_cndmask_b32_e64 v33, v34, v35, s[42:43]
	v_mul_f32_e32 v34, 0x37800000, v33
	v_cndmask_b32_e32 v33, v33, v34, vcc
	v_cmp_class_f32_e32 vcc, v32, v222
	s_nop 1
	v_cndmask_b32_e32 v32, v33, v32, vcc
	v_div_scale_f32 v33, s[8:9], v32, v32, 1.0
	v_rcp_f32_e32 v34, v33
	s_nop 0
	v_fma_f32 v35, -v33, v34, 1.0
	v_fmac_f32_e32 v34, v35, v34
	v_div_scale_f32 v35, vcc, 1.0, v32, 1.0
	v_mul_f32_e32 v41, v35, v34
	v_fma_f32 v42, -v33, v41, v35
	v_fmac_f32_e32 v41, v42, v34
	v_fma_f32 v33, -v33, v41, v35
	v_div_fmas_f32 v33, v33, v34, v41
	v_div_fixup_f32 v94, v33, v32, 1.0
	v_mov_b64_e32 v[32:33], v[160:161]
	v_mov_b64_e32 v[34:35], v[162:163]
	v_pk_mul_f32 v[90:91], v[90:91], v[40:41] op_sel_hi:[1,0]
	v_pk_mul_f32 v[92:93], v[92:93], v[40:41] op_sel_hi:[1,0]
	v_lshl_add_u64 v[42:43], v[70:71], 0, s[48:49]
	v_mov_b32_e32 v95, v94
	v_pk_mul_f32 v[92:93], v[34:35], v[92:93]
	v_pk_mul_f32 v[90:91], v[32:33], v[90:91]
	s_nop 0
	v_cvt_pk_bf16_f32 v90, v90, v91
	v_cvt_pk_bf16_f32 v91, v92, v93
	global_store_dwordx2 v[98:99], v[90:91], off
	s_cbranch_scc1 .LBB0_704
	v_mov_b32_e32 v90, v94
	v_mov_b32_e32 v91, v94
	v_pk_mul_f32 v[56:57], v[56:57], v[90:91]
	v_pk_mul_f32 v[58:59], v[58:59], v[94:95]
	v_pk_mul_f32 v[34:35], v[34:35], v[56:57]
	v_pk_mul_f32 v[32:33], v[32:33], v[58:59]
	s_nop 0
	v_cvt_pk_bf16_f32 v32, v32, v33
	v_cvt_pk_bf16_f32 v33, v34, v35
	global_store_dwordx2 v[42:43], v[32:33], off
.LBB0_704:
	v_mov_b64_e32 v[32:33], v[164:165]
	v_mov_b64_e32 v[34:35], v[166:167]
	v_mov_b32_e32 v41, v40
	v_mov_b32_e32 v56, v40
	v_mov_b32_e32 v57, v40
	v_pk_mul_f32 v[58:59], v[60:61], v[56:57]
	v_pk_mul_f32 v[60:61], v[62:63], v[40:41]
	s_andn2_b64 vcc, exec, s[16:17]
	v_pk_mul_f32 v[58:59], v[58:59], v[34:35]
	v_pk_mul_f32 v[60:61], v[60:61], v[32:33]
	s_nop 0
	v_cvt_pk_bf16_f32 v60, v60, v61
	v_cvt_pk_bf16_f32 v61, v58, v59
	v_cndmask_b32_e64 v58, 0, 1, s[16:17]
	v_cmp_ne_u32_e64 s[42:43], 1, v58
	global_store_dwordx2 v[98:99], v[60:61], off offset:512
	s_cbranch_vccnz .LBB0_706
	v_mov_b32_e32 v58, v94
	v_mov_b32_e32 v59, v94
	v_pk_mul_f32 v[48:49], v[48:49], v[58:59]
	v_pk_mul_f32 v[50:51], v[50:51], v[94:95]
	v_pk_mul_f32 v[34:35], v[48:49], v[34:35]
	v_pk_mul_f32 v[32:33], v[50:51], v[32:33]
	s_nop 0
	v_cvt_pk_bf16_f32 v32, v32, v33
	v_cvt_pk_bf16_f32 v33, v34, v35
	global_store_dwordx2 v[42:43], v[32:33], off offset:512
.LBB0_706:
	v_mov_b64_e32 v[32:33], v[168:169]
	v_mov_b64_e32 v[34:35], v[170:171]
	v_pk_mul_f32 v[48:49], v[52:53], v[56:57]
	v_pk_mul_f32 v[50:51], v[54:55], v[40:41]
	s_and_b64 vcc, exec, s[42:43]
	v_pk_mul_f32 v[48:49], v[48:49], v[34:35]
	v_pk_mul_f32 v[50:51], v[50:51], v[32:33]
	s_nop 0
	v_cvt_pk_bf16_f32 v50, v50, v51
	v_cvt_pk_bf16_f32 v51, v48, v49
	global_store_dwordx2 v[98:99], v[50:51], off offset:1024
	s_cbranch_vccnz .LBB0_708
	v_mov_b32_e32 v48, v94
	v_mov_b32_e32 v49, v94
	v_pk_mul_f32 v[46:47], v[46:47], v[48:49]
	v_pk_mul_f32 v[44:45], v[44:45], v[94:95]
	v_pk_mul_f32 v[34:35], v[46:47], v[34:35]
	v_pk_mul_f32 v[32:33], v[44:45], v[32:33]
	s_nop 0
	v_cvt_pk_bf16_f32 v32, v32, v33
	v_cvt_pk_bf16_f32 v33, v34, v35
	global_store_dwordx2 v[42:43], v[32:33], off offset:1024
.LBB0_708:
	v_mov_b64_e32 v[32:33], v[172:173]
	v_mov_b64_e32 v[34:35], v[174:175]
	v_mov_b32_e32 v44, v40
	v_mov_b32_e32 v45, v40
	v_pk_mul_f32 v[40:41], v[100:101], v[40:41]
	v_pk_mul_f32 v[44:45], v[96:97], v[44:45]
	s_and_b64 vcc, exec, s[42:43]
	v_pk_mul_f32 v[44:45], v[44:45], v[34:35]
	v_pk_mul_f32 v[40:41], v[40:41], v[32:33]
	s_nop 0
	v_cvt_pk_bf16_f32 v40, v40, v41
	v_cvt_pk_bf16_f32 v41, v44, v45
	global_store_dwordx2 v[98:99], v[40:41], off offset:1536
	s_cbranch_vccnz .LBB0_699
	v_mov_b32_e32 v40, v94
	v_mov_b32_e32 v41, v94
	v_pk_mul_f32 v[36:37], v[36:37], v[40:41]
	v_pk_mul_f32 v[38:39], v[38:39], v[94:95]
	v_pk_mul_f32 v[34:35], v[36:37], v[34:35]
	v_pk_mul_f32 v[32:33], v[38:39], v[32:33]
	s_nop 0
	v_cvt_pk_bf16_f32 v32, v32, v33
	v_cvt_pk_bf16_f32 v33, v34, v35
	global_store_dwordx2 v[42:43], v[32:33], off offset:1536
	s_branch .LBB0_699

; __device__ __forceinline__ void row_load(f32x4 (&v)[2][4], v2u (&w)[2][4], v2u (&w2)[2][4], const bf16* m1, const bf16* m2, const float* xin, int row, int NGW, int lane) {
;     const int row2 = (row + NGW) < TOK ? row + NGW : row;
;     const f32x4* xr0 = (const f32x4*)(xin + (size_t)row * DM) + lane; const f32x4* xr1 = (const f32x4*)(xin + (size_t)row2 * DM) + lane;
; #pragma unroll
;     for (int j = 0; j < 4; ++j) { v[0][j] = __builtin_nontemporal_load(xr0 + 64 * j); v[1][j] = __builtin_nontemporal_load(xr1 + 64 * j); }
;     if (m1) { const v2u* mr0 = (const v2u*)(m1 + (size_t)row * DM) + lane; const v2u* mr1 = (const v2u*)(m1 + (size_t)row2 * DM) + lane;
; #pragma unroll
;         for (int j = 0; j < 4; ++j) { w[0][j] = __builtin_nontemporal_load(mr0 + 64 * j); w[1][j] = __builtin_nontemporal_load(mr1 + 64 * j); } }
;     if (m2) { const v2u* mr0 = (const v2u*)(m2 + (size_t)row * DM) + lane; const v2u* mr1 = (const v2u*)(m2 + (size_t)row2 * DM) + lane;
; #pragma unroll
;         for (int j = 0; j < 4; ++j) { w2[0][j] = __builtin_nontemporal_load(mr0 + 64 * j); w2[1][j] = __builtin_nontemporal_load(mr1 + 64 * j); } }
; }
; __device__ __forceinline__ void row_add_norm(f32x4 (&v)[2][4], const v2u (&w)[2][4], const float* g, int lane) {
;     f32x4 m0[4], m1[4]; float s0 = 0.f, s1 = 0.f;
; #pragma unroll
;     for (int j = 0; j < 4; ++j) { m0[j] = (f32x4){pg8::bf_lo(w[0][j].x), pg8::bf_hi(w[0][j].x), pg8::bf_lo(w[0][j].y), pg8::bf_hi(w[0][j].y)}; m1[j] = (f32x4){pg8::bf_lo(w[1][j].x), pg8::bf_hi(w[1][j].x), pg8::bf_lo(w[1][j].y), pg8::bf_hi(w[1][j].y)};
;         s0 += (m0[j][0] * m0[j][0] + m0[j][1] * m0[j][1]) + (m0[j][2] * m0[j][2] + m0[j][3] * m0[j][3]); s1 += (m1[j][0] * m1[j][0] + m1[j][1] * m1[j][1]) + (m1[j][2] * m1[j][2] + m1[j][3] * m1[j][3]); }
;     const float r0 = 1.0f / sqrtf(wave_sum(s0) * (1.0f / DM) + 1e-6f), r1 = 1.0f / sqrtf(wave_sum(s1) * (1.0f / DM) + 1e-6f);
; #pragma unroll
;     for (int j = 0; j < 4; ++j) { const f32x4 gg = ((const f32x4*)g)[64 * j + lane]; v[0][j] = v[0][j] + m0[j] * r0 * gg; v[1][j] = v[1][j] + m1[j] * r1 * gg; }
; }
; __device__ __forceinline__ void row_phase(const bf16* m1, const float* g1, const bf16* m2, const float* g2, const float* xin, float* xout, const float* gpre, bf16* hout, int gw, int NGW, int lane_in) {
;     int lane = lane_in; asm volatile("" : "+v"(lane));
.LBB0_926:
	v_readlane_b32 s0, v255, 39
	v_readlane_b32 s1, v255, 40
	v_mov_b32_e32 v0, v219
	s_and_b64 vcc, exec, s[0:1]
	s_cbranch_vccnz .LBB0_945
	v_readlane_b32 s0, v255, 37
	v_readlane_b32 s1, v255, 38
	s_and_b64 s[0:1], s[0:1], exec
	s_load_dwordx4 s[8:11], s[56:57], 0x38
	s_load_dwordx4 s[48:51], s[56:57], 0x60
	s_cselect_b32 s0, 0, 0x68
	s_add_u32 s0, s56, s0
	s_addc_u32 s1, s57, 0
	s_lshl_b32 s12, s62, 10
	s_mov_b32 s13, s25
	s_lshl_b64 s[12:13], s[12:13], 2
	s_load_dwordx2 s[16:17], s[56:57], 0x70
	s_nop 0
	s_load_dwordx2 s[0:1], s[0:1], 0x0
	s_waitcnt lgkmcnt(0)
	s_add_u32 s22, s8, s12
	s_addc_u32 s23, s9, s13
	s_lshl_b64 s[8:9], s[24:25], 2
	s_add_u32 s12, s48, s8
	s_addc_u32 s13, s49, s9
	s_add_u32 s20, s16, 0xc000000
	s_addc_u32 s21, s17, 0
	s_add_u32 s8, s10, s8
	s_addc_u32 s9, s11, s9
	v_readlane_b32 s14, v254, 58
	s_add_u32 s10, s16, 0x10000000
	v_readlane_b32 s15, v254, 59
	s_addc_u32 s11, s17, 0
	s_lshl_b64 s[30:31], s[14:15], 2
	s_add_u32 s30, s0, s30
	v_ashrrev_i32_e32 v1, 31, v0
	v_readlane_b32 s40, v254, 60
	s_addc_u32 s31, s1, s31
	v_lshlrev_b64 v[2:3], 4, v[0:1]
	v_readlane_b32 s41, v254, 61
	v_lshl_add_u64 v[4:5], s[30:31], 0, v[2:3]
	s_lshl_b64 s[30:31], s[40:41], 2
	s_add_u32 s30, s0, s30
	s_addc_u32 s31, s1, s31
	v_lshl_add_u64 v[6:7], s[30:31], 0, v[2:3]
	s_lshl_b64 s[30:31], s[14:15], 1
	s_add_u32 s38, s10, s30
	s_addc_u32 s39, s11, s31
	v_lshlrev_b64 v[0:1], 3, v[0:1]
	global_load_dwordx4 v[56:59], v[4:5], off nt
	global_load_dwordx4 v[48:51], v[4:5], off offset:1024 nt
	global_load_dwordx4 v[60:63], v[6:7], off nt
	global_load_dwordx4 v[52:55], v[6:7], off offset:1024 nt
	global_load_dwordx4 v[40:43], v[4:5], off offset:2048 nt
	global_load_dwordx4 v[36:39], v[4:5], off offset:3072 nt
	global_load_dwordx4 v[44:47], v[6:7], off offset:2048 nt
	global_load_dwordx4 v[32:35], v[6:7], off offset:3072 nt
	v_lshl_add_u64 v[4:5], s[38:39], 0, v[0:1]
	s_lshl_b64 s[38:39], s[40:41], 1
	s_add_u32 s40, s10, s38
	s_addc_u32 s41, s11, s39
	s_add_u32 s30, s20, s30
	s_addc_u32 s31, s21, s31
	v_lshl_add_u64 v[6:7], s[40:41], 0, v[0:1]
	global_load_dwordx2 v[138:139], v[4:5], off nt
	global_load_dwordx2 v[136:137], v[4:5], off offset:512 nt
	global_load_dwordx2 v[130:131], v[4:5], off offset:1024 nt
	global_load_dwordx2 v[142:143], v[4:5], off offset:1536 nt
	global_load_dwordx2 v[134:135], v[6:7], off nt
	global_load_dwordx2 v[128:129], v[6:7], off offset:512 nt
	global_load_dwordx2 v[144:145], v[6:7], off offset:1024 nt
	global_load_dwordx2 v[140:141], v[6:7], off offset:1536 nt
	v_lshl_add_u64 v[4:5], s[30:31], 0, v[0:1]
	s_add_u32 s30, s20, s38
	s_addc_u32 s31, s21, s39
	v_lshl_add_u64 v[6:7], s[30:31], 0, v[0:1]
	global_load_dwordx2 v[126:127], v[4:5], off nt
	global_load_dwordx2 v[122:123], v[4:5], off offset:512 nt
	global_load_dwordx2 v[70:71], v[4:5], off offset:1024 nt
	global_load_dwordx2 v[66:67], v[4:5], off offset:1536 nt
	global_load_dwordx2 v[124:125], v[6:7], off nt
	global_load_dwordx2 v[120:121], v[6:7], off offset:512 nt
	global_load_dwordx2 v[68:69], v[6:7], off offset:1024 nt
	global_load_dwordx2 v[64:65], v[6:7], off offset:1536 nt
	v_lshl_add_u64 v[72:73], s[0:1], 0, v[2:3]
	v_lshl_add_u64 v[74:75], s[10:11], 0, v[0:1]
	v_lshl_add_u64 v[76:77], s[20:21], 0, v[0:1]
	s_cmp_lg_u64 s[50:51], 0
	v_lshl_add_u64 v[0:1], s[16:17], 0, v[0:1]
	s_mov_b64 s[0:1], 0x18000000
	v_lshl_add_u64 v[78:79], s[8:9], 0, v[2:3]
	v_lshl_add_u64 v[80:81], s[12:13], 0, v[2:3]
	s_cselect_b64 s[42:43], -1, 0
	v_lshl_add_u64 v[82:83], s[50:51], 0, v[2:3]
	v_lshl_add_u64 v[84:85], v[0:1], 0, s[0:1]
	v_lshl_add_u64 v[86:87], s[22:23], 0, v[2:3]
	v_readlane_b32 s48, v254, 56
	v_readlane_b32 s49, v254, 57
	v_and_b32_e32 v252, 63, v218
	v_lshlrev_b32_e32 v252, 4, v252
	v_lshrrev_b32_e32 v253, 6, v218
	v_lshl_or_b32 v252, v253, 14, v252
	global_load_dwordx4 v[198:201], v[86:87], off
	global_load_dwordx4 v[202:205], v[86:87], off offset:1024
	global_load_dwordx4 v[206:209], v[86:87], off offset:2048
	global_load_dwordx4 v[210:213], v[86:87], off offset:3072
	s_waitcnt vmcnt(0)
	ds_write_b128 v252, v[198:201]
	ds_write_b128 v252, v[202:205] offset:1024
	ds_write_b128 v252, v[206:209] offset:2048
	ds_write_b128 v252, v[210:213] offset:3072
	s_waitcnt lgkmcnt(0)
	global_load_dwordx4 v[198:201], v[78:79], off
	global_load_dwordx4 v[202:205], v[78:79], off offset:1024
	global_load_dwordx4 v[206:209], v[78:79], off offset:2048
	global_load_dwordx4 v[210:213], v[78:79], off offset:3072
	global_load_dwordx4 v[232:235], v[80:81], off
	global_load_dwordx4 v[236:239], v[80:81], off offset:1024
	global_load_dwordx4 v[240:243], v[80:81], off offset:2048
	global_load_dwordx4 v[244:247], v[80:81], off offset:3072
	s_waitcnt vmcnt(0)
	s_branch .LBB0_929
.LBB0_928:
	s_waitcnt vmcnt(8)
	s_add_i32 s48, s16, s33
	v_mov_b64_e32 v[34:35], v[18:19]
	s_cmpk_gt_i32 s48, 0x7fff
	v_mov_b64_e32 v[140:141], v[94:95]
	v_mov_b64_e32 v[144:145], v[96:97]
	v_mov_b64_e32 v[128:129], v[98:99]
	v_mov_b64_e32 v[134:135], v[100:101]
	v_mov_b64_e32 v[142:143], v[102:103]
	v_mov_b64_e32 v[130:131], v[92:93]
	v_mov_b64_e32 v[136:137], v[90:91]
	v_mov_b64_e32 v[138:139], v[88:89]
	v_mov_b64_e32 v[64:65], v[110:111]
	v_mov_b64_e32 v[68:69], v[112:113]
	v_mov_b64_e32 v[120:121], v[114:115]
	v_mov_b64_e32 v[124:125], v[116:117]
	v_mov_b64_e32 v[66:67], v[118:119]
	v_mov_b64_e32 v[70:71], v[108:109]
	v_mov_b64_e32 v[122:123], v[106:107]
	v_mov_b64_e32 v[126:127], v[104:105]
	v_mov_b64_e32 v[32:33], v[16:17]
	v_mov_b32_e32 v56, v8
	v_mov_b32_e32 v57, v9
	v_mov_b32_e32 v58, v10
	v_mov_b32_e32 v59, v11
	v_mov_b32_e32 v48, v12
	v_mov_b32_e32 v49, v13
	v_mov_b32_e32 v50, v14
	v_mov_b32_e32 v51, v15
	v_mov_b32_e32 v40, v24
	v_mov_b32_e32 v41, v25
	v_mov_b32_e32 v42, v26
	v_mov_b32_e32 v43, v27
	v_mov_b32_e32 v36, v28
	v_mov_b32_e32 v37, v29
	v_mov_b32_e32 v38, v30
	v_mov_b32_e32 v39, v31
	v_mov_b32_e32 v60, v4
	v_mov_b32_e32 v61, v5
	v_mov_b32_e32 v62, v6
	v_mov_b32_e32 v63, v7
	v_mov_b32_e32 v52, v0
	v_mov_b32_e32 v53, v1
	v_mov_b32_e32 v54, v2
	v_mov_b32_e32 v55, v3
	v_mov_b32_e32 v44, v20
	v_mov_b32_e32 v45, v21
	v_mov_b32_e32 v46, v22
	v_mov_b32_e32 v47, v23
	s_cbranch_scc1 .LBB0_945

; __device__ __forceinline__ float bf_lo(unsigned w) { return __uint_as_float(w << 16); }
; __device__ __forceinline__ float bf_hi(unsigned w) { return __uint_as_float(w & 0xffff0000u); }
; __device__ __forceinline__ void row_add_norm(f32x4 (&v)[2][4], const v2u (&w)[2][4], const float* g, int lane) {
;     f32x4 m0[4], m1[4]; float s0 = 0.f, s1 = 0.f;
; #pragma unroll
;     for (int j = 0; j < 4; ++j) { m0[j] = (f32x4){pg8::bf_lo(w[0][j].x), pg8::bf_hi(w[0][j].x), pg8::bf_lo(w[0][j].y), pg8::bf_hi(w[0][j].y)}; m1[j] = (f32x4){pg8::bf_lo(w[1][j].x), pg8::bf_hi(w[1][j].x), pg8::bf_lo(w[1][j].y), pg8::bf_hi(w[1][j].y)};
;         s0 += (m0[j][0] * m0[j][0] + m0[j][1] * m0[j][1]) + (m0[j][2] * m0[j][2] + m0[j][3] * m0[j][3]); s1 += (m1[j][0] * m1[j][0] + m1[j][1] * m1[j][1]) + (m1[j][2] * m1[j][2] + m1[j][3] * m1[j][3]); }
;     const float r0 = 1.0f / sqrtf(wave_sum(s0) * (1.0f / DM) + 1e-6f), r1 = 1.0f / sqrtf(wave_sum(s1) * (1.0f / DM) + 1e-6f);
; #pragma unroll
;     for (int j = 0; j < 4; ++j) { const f32x4 gg = ((const f32x4*)g)[64 * j + lane]; v[0][j] = v[0][j] + m0[j] * r0 * gg; v[1][j] = v[1][j] + m1[j] * r1 * gg; }
; }
.LBB0_931:
	v_and_b32_e32 v163, 0xffff0000, v135
	v_and_b32_e32 v162, 0xffff0000, v134
	v_lshlrev_b32_e32 v159, 16, v135
	v_lshlrev_b32_e32 v158, 16, v134
	v_pk_mul_f32 v[134:135], v[162:163], v[162:163]
	v_lshlrev_b32_e32 v154, 16, v136
	v_pk_fma_f32 v[134:135], v[158:159], v[158:159], v[134:135]
	v_and_b32_e32 v155, 0xffff0000, v137
	v_pk_add_f32 v[166:167], v[134:135], v[134:135] op_sel_hi:[0,1]
	v_and_b32_e32 v134, 0xffff0000, v136
	v_lshlrev_b32_e32 v135, 16, v137
	v_pk_mul_f32 v[136:137], v[134:135], v[134:135]
	v_and_b32_e32 v157, 0xffff0000, v129
	v_and_b32_e32 v156, 0xffff0000, v128
	v_pk_fma_f32 v[136:137], v[154:155], v[154:155], v[136:137]
	v_lshlrev_b32_e32 v153, 16, v129
	v_lshlrev_b32_e32 v152, 16, v128
	v_pk_mul_f32 v[128:129], v[156:157], v[156:157]
	v_pk_add_f32 v[168:169], v[136:137], v[136:137] op_sel_hi:[0,1]
	v_pk_fma_f32 v[128:129], v[152:153], v[152:153], v[128:129]
	v_lshlrev_b32_e32 v136, 16, v130
	v_and_b32_e32 v148, 0xffff0000, v131
	v_pk_add_f32 v[170:171], v[128:129], v[128:129] op_sel_hi:[0,1]
	v_mul_f32_e32 v129, v136, v136
	v_lshlrev_b32_e32 v149, 16, v131
	v_mul_f32_e32 v128, v148, v148
	v_lshlrev_b32_e32 v150, 16, v145
	v_and_b32_e32 v132, 0xffff0000, v138
	v_lshlrev_b32_e32 v133, 16, v139
	v_pk_fma_f32 v[174:175], v[148:149], v[148:149], v[128:129] op_sel_hi:[1,1,0]
	v_and_b32_e32 v151, 0xffff0000, v145
	v_mul_f32_e32 v128, v150, v150
	v_lshlrev_b32_e32 v160, 16, v138
	v_and_b32_e32 v161, 0xffff0000, v139
	v_pk_mul_f32 v[138:139], v[132:133], v[132:133]
	v_and_b32_e32 v137, 0xffff0000, v130
	v_pk_fma_f32 v[178:179], v[150:151], v[150:151], v[128:129] op_sel_hi:[1,1,0]
	v_lshlrev_b32_e32 v128, 16, v142
	v_pk_fma_f32 v[138:139], v[160:161], v[160:161], v[138:139]
	v_mul_f32_e32 v173, v137, v137
	v_mov_b32_e32 v172, v128
	v_pk_add_f32 v[164:165], v[138:139], v[138:139] op_sel_hi:[0,1]
	v_and_b32_e32 v147, 0xffff0000, v142
	v_lshlrev_b32_e32 v142, 16, v143
	v_and_b32_e32 v143, 0xffff0000, v143
	v_pk_add_f32 v[172:173], v[128:129], v[172:173]
	v_mul_f32_e32 v174, v147, v147
	v_mul_f32_e32 v164, v142, v142
	v_mul_f32_e32 v168, v143, v143
	v_mul_f32_e32 v180, v128, v128
	v_mov_b32_e32 v181, v173
	v_pk_add_f32 v[172:173], v[180:181], v[174:175]
	v_pk_add_f32 v[164:165], v[168:169], v[164:165]
	v_lshlrev_b32_e32 v138, 16, v144
	v_pk_add_f32 v[164:165], v[172:173], v[164:165]
	v_and_b32_e32 v139, 0xffff0000, v144
	v_add_f32_e32 v129, v164, v165
	ds_bpermute_b32 v144, v226, v129
	v_lshlrev_b32_e32 v130, 16, v140
	v_mul_f32_e32 v131, v138, v138
	v_mul_f32_e32 v177, v139, v139
	v_mov_b32_e32 v176, v130
	s_waitcnt lgkmcnt(0)
	v_add_f32_e32 v129, v129, v144
	ds_bpermute_b32 v144, v227, v129
	v_and_b32_e32 v145, 0xffff0000, v140
	v_lshlrev_b32_e32 v140, 16, v141
	v_and_b32_e32 v141, 0xffff0000, v141
	v_pk_add_f32 v[168:169], v[130:131], v[176:177]
	s_waitcnt lgkmcnt(0)
	v_add_f32_e32 v129, v129, v144
	ds_bpermute_b32 v144, v228, v129
	v_mul_f32_e32 v178, v145, v145
	v_mul_f32_e32 v170, v140, v140
	v_mul_f32_e32 v166, v141, v141
	v_mul_f32_e32 v164, v130, v130
	s_waitcnt lgkmcnt(0)
	v_add_f32_e32 v129, v129, v144
	ds_bpermute_b32 v144, v229, v129
	v_mov_b32_e32 v165, v169
	v_pk_add_f32 v[164:165], v[164:165], v[178:179]
	v_pk_add_f32 v[166:167], v[170:171], v[166:167]
	v_mov_b32_e32 v168, v133
	s_waitcnt lgkmcnt(0)
	v_add_f32_e32 v129, v129, v144
	ds_bpermute_b32 v144, v230, v129
	v_pk_add_f32 v[164:165], v[164:165], v[166:167]
	v_mov_b32_e32 v169, v161
	v_add_f32_e32 v131, v164, v165
	v_mov_b32_e32 v161, v132
	s_waitcnt lgkmcnt(0)
	v_add_f32_e32 v129, v129, v144
	ds_bpermute_b32 v144, v231, v129
	s_add_i32 s16, s48, s33
	s_cmp_lt_i32 s16, 0x8000
	s_cselect_b64 s[22:23], -1, 0
	s_cmpk_gt_i32 s16, 0x7fff
	s_waitcnt lgkmcnt(0)
	v_add_f32_e32 v129, v129, v144
	v_fmamk_f32 v129, v129, 0x3a800000, v223
	v_cmp_gt_f32_e32 vcc, s64, v129
	v_mul_f32_e32 v144, 0x4f800000, v129
	s_cselect_b64 s[50:51], -1, 0
	v_cndmask_b32_e32 v129, v129, v144, vcc
	v_sqrt_f32_e32 v144, v129
	s_ashr_i32 s49, s48, 31
	v_add_u32_e32 v146, -1, v144
	v_fma_f32 v164, -v146, v144, v129
	v_cmp_ge_f32_e64 s[38:39], 0, v164
	v_add_u32_e32 v164, 1, v144
	s_nop 0
	v_cndmask_b32_e64 v146, v144, v146, s[38:39]
	v_fma_f32 v144, -v164, v144, v129
	v_cmp_lt_f32_e64 s[38:39], 0, v144
	s_nop 1
	v_cndmask_b32_e64 v144, v146, v164, s[38:39]
	v_mul_f32_e32 v146, 0x37800000, v144
	v_cndmask_b32_e32 v144, v144, v146, vcc
	v_cmp_class_f32_e32 vcc, v129, v222
	s_nop 1
	v_cndmask_b32_e32 v129, v144, v129, vcc
	v_div_scale_f32 v144, s[0:1], v129, v129, 1.0
	v_rcp_f32_e32 v146, v144
	s_nop 0
	v_fma_f32 v164, -v144, v146, 1.0
	v_fmac_f32_e32 v146, v164, v146
	v_div_scale_f32 v164, vcc, 1.0, v129, 1.0
	v_mul_f32_e32 v165, v164, v146
	v_fma_f32 v166, -v144, v165, v164
	v_fmac_f32_e32 v165, v166, v146
	v_fma_f32 v144, -v144, v165, v164
	v_div_fmas_f32 v144, v144, v146, v165
	v_div_fixup_f32 v144, v144, v129, 1.0
	ds_bpermute_b32 v129, v226, v131
	v_pk_mul_f32 v[168:169], v[144:145], v[168:169] op_sel_hi:[0,1]
	v_pk_mul_f32 v[132:133], v[144:145], v[160:161] op_sel_hi:[0,1]
	s_waitcnt lgkmcnt(0)
	v_add_f32_e32 v129, v131, v129
	ds_bpermute_b32 v131, v227, v129
	s_waitcnt lgkmcnt(0)
	v_add_f32_e32 v129, v129, v131
	ds_bpermute_b32 v131, v228, v129
	s_waitcnt lgkmcnt(0)
	v_add_f32_e32 v129, v129, v131
	ds_bpermute_b32 v131, v229, v129
	s_waitcnt lgkmcnt(0)
	v_add_f32_e32 v129, v129, v131
	ds_bpermute_b32 v131, v230, v129
	s_waitcnt lgkmcnt(0)
	v_add_f32_e32 v129, v129, v131
	ds_bpermute_b32 v131, v231, v129
	s_waitcnt lgkmcnt(0)
; __device__ __forceinline__ void row_add_norm(f32x4 (&v)[2][4], const v2u (&w)[2][4], const float* g, int lane) {
;     ...
;     const float r0 = 1.0f / sqrtf(wave_sum(s0) * (1.0f / DM) + 1e-6f), r1 = 1.0f / sqrtf(wave_sum(s1) * (1.0f / DM) + 1e-6f);
; #pragma unroll
;     for (int j = 0; j < 4; ++j) { const f32x4 gg = ((const f32x4*)g)[64 * j + lane]; v[0][j] = v[0][j] + m0[j] * r0 * gg; v[1][j] = v[1][j] + m1[j] * r1 * gg; }
; }
; __device__ __forceinline__ void row_phase(const bf16* m1, const float* g1, const bf16* m2, const float* g2, const float* xin, float* xout, const float* gpre, bf16* hout, int gw, int NGW, int lane_in) {
;     int lane = lane_in; asm volatile("" : "+v"(lane));
;     f32x4 v[2][4]; v2u w[2][4], w2[2][4];
;     if (gw < TOK) row_load(v, w, w2, m1, m2, xin, gw, NGW, lane);
;     for (int row = gw; row < TOK; row += 2 * NGW) {
;         const bool two = (row + NGW) < TOK; const int row2 = two ? row + NGW : row;
;         f32x4 nv[2][4]; v2u nw[2][4], nw2[2][4];
;         const int nrow = row + 2 * NGW;
;         if (nrow < TOK) row_load(nv, nw, nw2, m1, m2, xin, nrow, NGW, lane);
;         if (m1) row_add_norm(v, w, g1, lane);
;         if (m2) row_add_norm(v, w2, g2, lane);
	v_add_f32_e32 v129, v129, v131
	v_fmamk_f32 v129, v129, 0x3a800000, v223
	v_cmp_gt_f32_e32 vcc, s64, v129
	v_mul_f32_e32 v131, 0x4f800000, v129
	s_nop 0
	v_cndmask_b32_e32 v129, v129, v131, vcc
	v_sqrt_f32_e32 v131, v129
	s_nop 0
	v_add_u32_e32 v146, -1, v131
	v_fma_f32 v164, -v146, v131, v129
	v_cmp_ge_f32_e64 s[38:39], 0, v164
	v_add_u32_e32 v164, 1, v131
	s_nop 0
	v_cndmask_b32_e64 v146, v131, v146, s[38:39]
	v_fma_f32 v131, -v164, v131, v129
	v_cmp_lt_f32_e64 s[38:39], 0, v131
	s_nop 1
	v_cndmask_b32_e64 v131, v146, v164, s[38:39]
	v_mul_f32_e32 v146, 0x37800000, v131
	v_cndmask_b32_e32 v131, v131, v146, vcc
	v_cmp_class_f32_e32 vcc, v129, v222
	s_nop 1
	v_cndmask_b32_e32 v129, v131, v129, vcc
	v_div_scale_f32 v131, s[0:1], v129, v129, 1.0
	v_rcp_f32_e32 v146, v131
	s_nop 0
	v_fma_f32 v164, -v131, v146, 1.0
	v_fmac_f32_e32 v146, v164, v146
	v_div_scale_f32 v164, vcc, 1.0, v129, 1.0
	v_mul_f32_e32 v165, v164, v146
	v_fma_f32 v166, -v131, v165, v164
	v_fmac_f32_e32 v165, v166, v146
	v_fma_f32 v131, -v131, v165, v164
	v_div_fmas_f32 v131, v131, v146, v165
	v_mov_b64_e32 v[164:165], v[198:199]
	v_mov_b64_e32 v[166:167], v[200:201]
	v_div_fixup_f32 v146, v131, v129, 1.0
	v_mov_b32_e32 v129, v147
	v_mov_b32_e32 v131, v145
	v_pk_fma_f32 v[56:57], v[164:165], v[132:133], v[56:57]
	v_pk_fma_f32 v[132:133], v[166:167], v[168:169], v[58:59]
	v_mov_b32_e32 v58, v159
	v_mov_b32_e32 v59, v163
	v_pk_mul_f32 v[160:161], v[146:147], v[58:59] op_sel_hi:[0,1]
	v_mov_b32_e32 v159, v162
	v_pk_mul_f32 v[58:59], v[146:147], v[158:159] op_sel_hi:[0,1]
	v_pk_fma_f32 v[62:63], v[166:167], v[160:161], v[62:63]
	v_mov_b64_e32 v[158:159], v[202:203]
	v_mov_b64_e32 v[160:161], v[204:205]
	v_pk_fma_f32 v[58:59], v[164:165], v[58:59], v[60:61]
	v_mov_b32_e32 v60, v135
	v_mov_b32_e32 v61, v155
	v_mov_b32_e32 v155, v134
	v_pk_mul_f32 v[60:61], v[144:145], v[60:61] op_sel_hi:[0,1]
	v_pk_mul_f32 v[134:135], v[144:145], v[154:155] op_sel_hi:[0,1]
	v_pk_fma_f32 v[48:49], v[158:159], v[134:135], v[48:49]
	v_pk_fma_f32 v[134:135], v[160:161], v[60:61], v[50:51]
	v_mov_b32_e32 v50, v153
	v_mov_b32_e32 v51, v157
	v_mov_b32_e32 v153, v156
	v_pk_mul_f32 v[60:61], v[146:147], v[50:51] op_sel_hi:[0,1]
	v_pk_mul_f32 v[50:51], v[146:147], v[152:153] op_sel_hi:[0,1]
	v_mov_b64_e32 v[152:153], v[206:207]
	v_mov_b64_e32 v[154:155], v[208:209]
	v_pk_fma_f32 v[50:51], v[158:159], v[50:51], v[52:53]
	v_pk_fma_f32 v[54:55], v[160:161], v[60:61], v[54:55]
	v_pk_mul_f32 v[60:61], v[148:149], v[144:145] op_sel:[1,0] op_sel_hi:[0,0]
	v_pk_mul_f32 v[52:53], v[136:137], v[144:145] op_sel_hi:[1,0]
	v_lshlrev_b32_e32 v149, 16, v121
	v_lshlrev_b32_e32 v148, 16, v120
	v_pk_fma_f32 v[52:53], v[152:153], v[52:53], v[40:41]
	v_pk_fma_f32 v[136:137], v[154:155], v[60:61], v[42:43]
	v_pk_mul_f32 v[40:41], v[150:151], v[146:147] op_sel_hi:[1,0]
	v_pk_mul_f32 v[42:43], v[138:139], v[146:147] op_sel_hi:[1,0]
	v_pk_fma_f32 v[138:139], v[154:155], v[40:41], v[46:47]
	v_pk_fma_f32 v[60:61], v[152:153], v[42:43], v[44:45]
	v_mov_b64_e32 v[40:41], v[210:211]
	v_mov_b64_e32 v[42:43], v[212:213]
	v_pk_mul_f32 v[44:45], v[142:143], v[144:145] op_sel_hi:[1,0]
	v_pk_mul_f32 v[46:47], v[128:129], v[144:145] op_sel_hi:[1,0]
	v_and_b32_e32 v151, 0xffff0000, v121
	v_and_b32_e32 v150, 0xffff0000, v120
	v_pk_mul_f32 v[120:121], v[150:151], v[150:151]
	v_and_b32_e32 v144, 0xffff0000, v71
	v_pk_fma_f32 v[120:121], v[148:149], v[148:149], v[120:121]
	v_lshlrev_b32_e32 v145, 16, v71
	v_pk_add_f32 v[154:155], v[120:121], v[120:121] op_sel_hi:[0,1]
	v_lshlrev_b32_e32 v120, 16, v66
	v_mov_b32_e32 v156, v120
	v_mul_f32_e32 v164, v120, v120
	v_pk_fma_f32 v[142:143], v[44:45], v[42:43], v[38:39]
	v_pk_mul_f32 v[38:39], v[130:131], v[146:147] op_sel_hi:[1,0]
	v_pk_fma_f32 v[128:129], v[46:47], v[40:41], v[36:37]
	v_pk_mul_f32 v[36:37], v[140:141], v[146:147] op_sel_hi:[1,0]
	v_pk_fma_f32 v[130:131], v[40:41], v[38:39], v[32:33]
	v_and_b32_e32 v32, 0xffff0000, v126
	v_lshlrev_b32_e32 v33, 16, v127
	v_pk_fma_f32 v[140:141], v[42:43], v[36:37], v[34:35]
	v_lshlrev_b32_e32 v34, 16, v126
	v_and_b32_e32 v35, 0xffff0000, v127
	v_pk_mul_f32 v[36:37], v[32:33], v[32:33]
	v_and_b32_e32 v40, 0xffff0000, v122
	v_pk_fma_f32 v[36:37], v[34:35], v[34:35], v[36:37]
	v_lshlrev_b32_e32 v41, 16, v123
	v_pk_add_f32 v[36:37], v[36:37], v[36:37] op_sel_hi:[0,1]
	v_lshlrev_b32_e32 v42, 16, v122
	v_and_b32_e32 v43, 0xffff0000, v123
	v_pk_mul_f32 v[122:123], v[40:41], v[40:41]
	v_lshlrev_b32_e32 v126, 16, v70
	v_and_b32_e32 v127, 0xffff0000, v70
	v_pk_fma_f32 v[122:123], v[42:43], v[42:43], v[122:123]
	v_mul_f32_e32 v121, v126, v126
	v_mul_f32_e32 v157, v127, v127
	v_mul_f32_e32 v36, v144, v144
	v_lshlrev_b32_e32 v146, 16, v69
	v_and_b32_e32 v47, 0xffff0000, v125
	v_and_b32_e32 v46, 0xffff0000, v124
	v_pk_add_f32 v[152:153], v[122:123], v[122:123] op_sel_hi:[0,1]
	v_pk_fma_f32 v[158:159], v[144:145], v[144:145], v[36:37] op_sel_hi:[1,1,0]
	v_and_b32_e32 v147, 0xffff0000, v69
	v_mul_f32_e32 v36, v146, v146
	v_and_b32_e32 v123, 0xffff0000, v66
	v_lshlrev_b32_e32 v66, 16, v67
	v_and_b32_e32 v67, 0xffff0000, v67
	v_pk_add_f32 v[156:157], v[120:121], v[156:157]
	v_lshlrev_b32_e32 v45, 16, v125
	v_lshlrev_b32_e32 v44, 16, v124
	v_pk_mul_f32 v[38:39], v[46:47], v[46:47]
	v_lshlrev_b32_e32 v124, 16, v68
	v_and_b32_e32 v125, 0xffff0000, v68
	v_pk_fma_f32 v[162:163], v[146:147], v[146:147], v[36:37] op_sel_hi:[1,1,0]
	v_lshlrev_b32_e32 v70, 16, v64
	v_mul_f32_e32 v158, v123, v123
	v_mul_f32_e32 v36, v66, v66
	v_mul_f32_e32 v152, v67, v67
	v_mov_b32_e32 v165, v157
	v_pk_fma_f32 v[38:39], v[44:45], v[44:45], v[38:39]
	v_mul_f32_e32 v71, v124, v124
	v_mul_f32_e32 v161, v125, v125
	v_pk_add_f32 v[156:157], v[164:165], v[158:159]
	v_pk_add_f32 v[36:37], v[152:153], v[36:37]
	v_mov_b32_e32 v160, v70
	v_pk_add_f32 v[38:39], v[38:39], v[38:39] op_sel_hi:[0,1]
	v_and_b32_e32 v69, 0xffff0000, v64
	v_lshlrev_b32_e32 v64, 16, v65
	v_and_b32_e32 v65, 0xffff0000, v65
	v_pk_add_f32 v[36:37], v[156:157], v[36:37]
	v_pk_add_f32 v[152:153], v[70:71], v[160:161]
	v_add_f32_e32 v68, v36, v37
	v_mul_f32_e32 v162, v69, v69
	v_mul_f32_e32 v154, v64, v64
	v_mul_f32_e32 v38, v65, v65
	v_mul_f32_e32 v36, v70, v70
	v_mov_b32_e32 v37, v153
	v_pk_add_f32 v[36:37], v[36:37], v[162:163]
	v_pk_add_f32 v[38:39], v[154:155], v[38:39]
	v_mov_b64_e32 v[152:153], v[232:233]
	v_mov_b64_e32 v[154:155], v[234:235]
	v_pk_add_f32 v[36:37], v[36:37], v[38:39]
	s_nop 0
	v_add_f32_e32 v36, v36, v37
	ds_bpermute_b32 v37, v226, v68
	s_waitcnt lgkmcnt(0)
; __device__ __forceinline__ float bf_lo(unsigned w) { return __uint_as_float(w << 16); }
; __device__ __forceinline__ float bf_hi(unsigned w) { return __uint_as_float(w & 0xffff0000u); }
; __device__ __forceinline__ void row_add_norm(f32x4 (&v)[2][4], const v2u (&w)[2][4], const float* g, int lane) {
;     f32x4 m0[4], m1[4]; float s0 = 0.f, s1 = 0.f;
; #pragma unroll
;     for (int j = 0; j < 4; ++j) { m0[j] = (f32x4){pg8::bf_lo(w[0][j].x), pg8::bf_hi(w[0][j].x), pg8::bf_lo(w[0][j].y), pg8::bf_hi(w[0][j].y)}; m1[j] = (f32x4){pg8::bf_lo(w[1][j].x), pg8::bf_hi(w[1][j].x), pg8::bf_lo(w[1][j].y), pg8::bf_hi(w[1][j].y)};
;         s0 += (m0[j][0] * m0[j][0] + m0[j][1] * m0[j][1]) + (m0[j][2] * m0[j][2] + m0[j][3] * m0[j][3]); s1 += (m1[j][0] * m1[j][0] + m1[j][1] * m1[j][1]) + (m1[j][2] * m1[j][2] + m1[j][3] * m1[j][3]); }
;     const float r0 = 1.0f / sqrtf(wave_sum(s0) * (1.0f / DM) + 1e-6f), r1 = 1.0f / sqrtf(wave_sum(s1) * (1.0f / DM) + 1e-6f);
; #pragma unroll
;     for (int j = 0; j < 4; ++j) { const f32x4 gg = ((const f32x4*)g)[64 * j + lane]; v[0][j] = v[0][j] + m0[j] * r0 * gg; v[1][j] = v[1][j] + m1[j] * r1 * gg; }
; }
; __device__ __forceinline__ void row_phase(const bf16* m1, const float* g1, const bf16* m2, const float* g2, const float* xin, float* xout, const float* gpre, bf16* hout, int gw, int NGW, int lane_in) {
;     int lane = lane_in; asm volatile("" : "+v"(lane));
;     f32x4 v[2][4]; v2u w[2][4], w2[2][4];
;     if (gw < TOK) row_load(v, w, w2, m1, m2, xin, gw, NGW, lane);
;     for (int row = gw; row < TOK; row += 2 * NGW) {
;         const bool two = (row + NGW) < TOK; const int row2 = two ? row + NGW : row;
;         f32x4 nv[2][4]; v2u nw[2][4], nw2[2][4];
;         const int nrow = row + 2 * NGW;
;         if (nrow < TOK) row_load(nv, nw, nw2, m1, m2, xin, nrow, NGW, lane);
;         if (m1) row_add_norm(v, w, g1, lane);
;         if (m2) row_add_norm(v, w2, g2, lane);
;         if (xout) { f32x4* xo0 = (f32x4*)(xout + (size_t)row * DM) + lane; f32x4* xo1 = (f32x4*)(xout + (size_t)row2 * DM) + lane;
; #pragma unroll
;             for (int j = 0; j < 4; ++j) { __builtin_nontemporal_store(v[0][j], xo0 + 64 * j); if (two) __builtin_nontemporal_store(v[1][j], xo1 + 64 * j); } }
	v_add_f32_e32 v37, v68, v37
	ds_bpermute_b32 v38, v227, v37
	s_waitcnt lgkmcnt(0)
	v_add_f32_e32 v37, v37, v38
	ds_bpermute_b32 v38, v228, v37
	s_waitcnt lgkmcnt(0)
	v_add_f32_e32 v37, v37, v38
	ds_bpermute_b32 v38, v229, v37
	s_waitcnt lgkmcnt(0)
	v_add_f32_e32 v37, v37, v38
	ds_bpermute_b32 v38, v230, v37
	s_waitcnt lgkmcnt(0)
	v_add_f32_e32 v37, v37, v38
	ds_bpermute_b32 v38, v231, v37
	s_waitcnt lgkmcnt(0)
	v_add_f32_e32 v37, v37, v38
	v_fmamk_f32 v37, v37, 0x3a800000, v223
	v_cmp_gt_f32_e32 vcc, s64, v37
	v_mul_f32_e32 v38, 0x4f800000, v37
	s_nop 0
	v_cndmask_b32_e32 v37, v37, v38, vcc
	v_sqrt_f32_e32 v38, v37
	s_nop 0
	v_add_u32_e32 v39, -1, v38
	v_fma_f32 v68, -v39, v38, v37
	v_cmp_ge_f32_e64 s[38:39], 0, v68
	v_add_u32_e32 v68, 1, v38
	s_nop 0
	v_cndmask_b32_e64 v39, v38, v39, s[38:39]
	v_fma_f32 v38, -v68, v38, v37
	v_cmp_lt_f32_e64 s[38:39], 0, v38
	s_nop 1
	v_cndmask_b32_e64 v38, v39, v68, s[38:39]
	v_mul_f32_e32 v39, 0x37800000, v38
	v_cndmask_b32_e32 v38, v38, v39, vcc
	v_cmp_class_f32_e32 vcc, v37, v222
	s_nop 1
	v_cndmask_b32_e32 v37, v38, v37, vcc
	v_div_scale_f32 v38, s[0:1], v37, v37, 1.0
	v_rcp_f32_e32 v39, v38
	s_nop 0
	v_fma_f32 v68, -v38, v39, 1.0
	v_fmac_f32_e32 v39, v68, v39
	v_div_scale_f32 v68, vcc, 1.0, v37, 1.0
	v_mul_f32_e32 v71, v68, v39
	v_fma_f32 v121, -v38, v71, v68
	v_fmac_f32_e32 v71, v121, v39
	v_fma_f32 v38, -v38, v71, v68
	v_div_fmas_f32 v38, v38, v39, v71
	v_div_fixup_f32 v68, v38, v37, 1.0
	ds_bpermute_b32 v37, v226, v36
	s_waitcnt lgkmcnt(0)
	v_add_f32_e32 v36, v36, v37
	ds_bpermute_b32 v37, v227, v36
	s_waitcnt lgkmcnt(0)
	v_add_f32_e32 v36, v36, v37
	ds_bpermute_b32 v37, v228, v36
	s_waitcnt lgkmcnt(0)
	v_add_f32_e32 v36, v36, v37
	ds_bpermute_b32 v37, v229, v36
	s_waitcnt lgkmcnt(0)
	v_add_f32_e32 v36, v36, v37
	ds_bpermute_b32 v37, v230, v36
	s_waitcnt lgkmcnt(0)
	v_add_f32_e32 v36, v36, v37
	ds_bpermute_b32 v37, v231, v36
	s_waitcnt lgkmcnt(0)
	v_add_f32_e32 v36, v36, v37
	v_fmamk_f32 v36, v36, 0x3a800000, v223
	v_cmp_gt_f32_e32 vcc, s64, v36
	v_mul_f32_e32 v37, 0x4f800000, v36
	s_nop 0
	v_cndmask_b32_e32 v36, v36, v37, vcc
	v_sqrt_f32_e32 v37, v36
	s_nop 0
	v_add_u32_e32 v38, -1, v37
	v_fma_f32 v39, -v38, v37, v36
	v_cmp_ge_f32_e64 s[38:39], 0, v39
	v_add_u32_e32 v39, 1, v37
	s_nop 0
	v_cndmask_b32_e64 v38, v37, v38, s[38:39]
	v_fma_f32 v37, -v39, v37, v36
	v_cmp_lt_f32_e64 s[38:39], 0, v37
	s_nop 1
	v_cndmask_b32_e64 v37, v38, v39, s[38:39]
	v_mul_f32_e32 v38, 0x37800000, v37
	v_cndmask_b32_e32 v37, v37, v38, vcc
	v_cmp_class_f32_e32 vcc, v36, v222
	s_nop 1
	v_cndmask_b32_e32 v36, v37, v36, vcc
	v_div_scale_f32 v37, s[0:1], v36, v36, 1.0
	v_rcp_f32_e32 v38, v37
	s_nop 0
	v_fma_f32 v39, -v37, v38, 1.0
	v_fmac_f32_e32 v38, v39, v38
	v_div_scale_f32 v39, vcc, 1.0, v36, 1.0
	v_mul_f32_e32 v71, v39, v38
	v_fma_f32 v121, -v37, v71, v39
	v_fmac_f32_e32 v71, v121, v38
	v_fma_f32 v37, -v37, v71, v39
	v_div_fmas_f32 v37, v37, v38, v71
	v_div_fixup_f32 v122, v37, v36, 1.0
	v_mov_b32_e32 v36, v34
	v_mov_b32_e32 v34, v33
	v_mov_b32_e32 v37, v32
	v_pk_mul_f32 v[32:33], v[68:69], v[34:35] op_sel_hi:[0,1]
	v_pk_fma_f32 v[38:39], v[154:155], v[32:33], v[132:133]
	v_mov_b32_e32 v32, v44
	v_mov_b32_e32 v33, v46
	v_pk_mul_f32 v[36:37], v[68:69], v[36:37] op_sel_hi:[0,1]
	v_pk_mul_f32 v[32:33], v[122:123], v[32:33] op_sel_hi:[0,1]
	v_pk_fma_f32 v[36:37], v[152:153], v[36:37], v[56:57]
	v_pk_fma_f32 v[32:33], v[152:153], v[32:33], v[58:59]
	v_mov_b64_e32 v[56:57], v[236:237]
	v_mov_b64_e32 v[58:59], v[238:239]
	v_mov_b32_e32 v44, v42
	v_mov_b32_e32 v42, v41
	v_mov_b32_e32 v46, v45
	v_mov_b32_e32 v45, v40
	v_pk_mul_f32 v[40:41], v[68:69], v[42:43] op_sel_hi:[0,1]
	v_pk_mul_f32 v[34:35], v[122:123], v[46:47] op_sel_hi:[0,1]
	v_pk_mul_f32 v[44:45], v[68:69], v[44:45] op_sel_hi:[0,1]
	v_mov_b32_e32 v121, v123
	v_mov_b32_e32 v71, v69
	v_pk_fma_f32 v[34:35], v[154:155], v[34:35], v[62:63]
	v_pk_mul_f32 v[62:63], v[66:67], v[68:69] op_sel_hi:[1,0]
	v_pk_mul_f32 v[66:67], v[70:71], v[122:123] op_sel_hi:[1,0]
	v_pk_mul_f32 v[64:65], v[64:65], v[122:123] op_sel_hi:[1,0]
	s_andn2_b64 vcc, exec, s[42:43]
	v_pk_fma_f32 v[46:47], v[58:59], v[40:41], v[134:135]
	v_mov_b32_e32 v40, v148
	v_mov_b32_e32 v41, v150
	v_pk_mul_f32 v[40:41], v[122:123], v[40:41] op_sel_hi:[0,1]
	v_pk_fma_f32 v[44:45], v[56:57], v[44:45], v[48:49]
	v_pk_fma_f32 v[40:41], v[56:57], v[40:41], v[50:51]
	v_mov_b64_e32 v[48:49], v[240:241]
	v_mov_b64_e32 v[50:51], v[242:243]
	v_mov_b32_e32 v150, v149
	v_pk_mul_f32 v[42:43], v[122:123], v[150:151] op_sel_hi:[0,1]
	v_pk_mul_f32 v[56:57], v[126:127], v[68:69] op_sel_hi:[1,0]
	v_pk_fma_f32 v[42:43], v[58:59], v[42:43], v[54:55]
	v_pk_mul_f32 v[54:55], v[144:145], v[68:69] op_sel:[1,0] op_sel_hi:[0,0]
	v_pk_mul_f32 v[58:59], v[146:147], v[122:123] op_sel_hi:[1,0]
	v_pk_fma_f32 v[52:53], v[48:49], v[56:57], v[52:53]
	v_pk_mul_f32 v[56:57], v[124:125], v[122:123] op_sel_hi:[1,0]
	v_pk_fma_f32 v[54:55], v[50:51], v[54:55], v[136:137]
	v_pk_fma_f32 v[50:51], v[50:51], v[58:59], v[138:139]
	v_pk_fma_f32 v[48:49], v[48:49], v[56:57], v[60:61]
	v_mov_b64_e32 v[56:57], v[244:245]
	v_mov_b64_e32 v[58:59], v[246:247]
	v_pk_mul_f32 v[60:61], v[120:121], v[68:69] op_sel_hi:[1,0]
	v_pk_fma_f32 v[62:63], v[62:63], v[58:59], v[142:143]
	v_pk_fma_f32 v[60:61], v[60:61], v[56:57], v[128:129]
	v_pk_fma_f32 v[58:59], v[58:59], v[64:65], v[140:141]
	v_pk_fma_f32 v[56:57], v[56:57], v[66:67], v[130:131]
	s_cbranch_vccnz .LBB0_937
	s_lshl_b64 s[38:39], s[48:49], 12
	v_lshl_add_u64 v[120:121], v[82:83], 0, s[38:39]
	s_mov_b64 s[52:53], -1
	s_and_b64 vcc, exec, s[50:51]
	global_store_dwordx4 v[120:121], v[36:39], off nt
	s_cbranch_vccz .LBB0_934
	global_store_dwordx4 v[120:121], v[44:47], off offset:1024 nt
	s_mov_b64 s[52:53], 0

; __device__ __forceinline__ unsigned pk2(float lo, float hi) { return pg8::cvt_pk_bf16(lo, hi); }
; __device__ __forceinline__ void row_phase(const bf16* m1, const float* g1, const bf16* m2, const float* g2, const float* xin, float* xout, const float* gpre, bf16* hout, int gw, int NGW, int lane_in) {
;     ...
;         if (hout) {
;             float s0 = 0.f, s1 = 0.f;
; #pragma unroll
;             for (int j = 0; j < 4; ++j) { s0 += (v[0][j][0] * v[0][j][0] + v[0][j][1] * v[0][j][1]) + (v[0][j][2] * v[0][j][2] + v[0][j][3] * v[0][j][3]); s1 += (v[1][j][0] * v[1][j][0] + v[1][j][1] * v[1][j][1]) + (v[1][j][2] * v[1][j][2] + v[1][j][3] * v[1][j][3]); }
;             const float r0 = 1.0f / sqrtf(wave_sum(s0) * (1.0f / DM) + 1e-6f), r1 = 1.0f / sqrtf(wave_sum(s1) * (1.0f / DM) + 1e-6f);
;             v2u* ho0 = (v2u*)(hout + (size_t)row * DM) + lane; v2u* ho1 = (v2u*)(hout + (size_t)row2 * DM) + lane;
; #pragma unroll
;             for (int j = 0; j < 4; ++j) { const f32x4 g = ((const f32x4*)gpre)[64 * j + lane]; const f32x4 y0 = v[0][j] * r0 * g, y1 = v[1][j] * r1 * g;
;                 v2u a0, a1; a0.x = pk2(y0[0], y0[1]); a0.y = pk2(y0[2], y0[3]); a1.x = pk2(y1[0], y1[1]); a1.y = pk2(y1[2], y1[3]); ho0[64 * j] = a0; if (two) ho1[64 * j] = a1; }
.LBB0_937:
	v_pk_mul_f32 v[64:65], v[38:39], v[38:39]
	v_pk_mul_f32 v[66:67], v[36:37], v[36:37]
	s_and_b64 s[0:1], s[22:23], exec
	v_pk_mov_b32 v[68:69], v[66:67], v[64:65] op_sel:[1,0]
	v_mov_b32_e32 v67, v65
	v_pk_add_f32 v[64:65], v[68:69], v[66:67]
	v_pk_mul_f32 v[66:67], v[34:35], v[34:35]
	v_pk_mul_f32 v[68:69], v[32:33], v[32:33]
	v_pk_add_f32 v[64:65], v[64:65], v[64:65] op_sel_hi:[0,1]
	v_pk_mov_b32 v[70:71], v[68:69], v[66:67] op_sel:[1,0]
	v_mov_b32_e32 v69, v67
	v_pk_add_f32 v[66:67], v[70:71], v[68:69]
	v_pk_mul_f32 v[68:69], v[46:47], v[46:47]
	v_pk_mul_f32 v[70:71], v[44:45], v[44:45]
	v_mul_f32_e32 v64, v52, v52
	v_pk_mov_b32 v[120:121], v[70:71], v[68:69] op_sel:[1,0]
	v_mov_b32_e32 v71, v69
	v_pk_add_f32 v[68:69], v[120:121], v[70:71]
	v_pk_mul_f32 v[70:71], v[42:43], v[42:43]
	v_pk_mul_f32 v[120:121], v[40:41], v[40:41]
	v_pk_add_f32 v[68:69], v[68:69], v[68:69] op_sel_hi:[0,1]
	v_pk_mov_b32 v[122:123], v[120:121], v[70:71] op_sel:[1,0]
	v_mov_b32_e32 v121, v71
	v_pk_add_f32 v[70:71], v[122:123], v[120:121]
	v_pk_fma_f32 v[120:121], v[52:53], v[52:53], v[64:65] op_sel_hi:[1,1,0]
	v_mul_f32_e32 v64, v54, v54
	v_pk_fma_f32 v[122:123], v[54:55], v[54:55], v[64:65] op_sel_hi:[1,1,0]
	v_mul_f32_e32 v64, v48, v48
	v_pk_fma_f32 v[124:125], v[48:49], v[48:49], v[64:65] op_sel_hi:[1,1,0]
	v_mul_f32_e32 v64, v50, v50
	v_pk_fma_f32 v[126:127], v[50:51], v[50:51], v[64:65] op_sel_hi:[1,1,0]
	v_mul_f32_e32 v120, v60, v60
	v_mul_f32_e32 v122, v61, v61
	v_mul_f32_e32 v64, v62, v62
	v_mul_f32_e32 v68, v63, v63
	v_pk_add_f32 v[66:67], v[66:67], v[66:67] op_sel_hi:[0,1]
	v_pk_add_f32 v[70:71], v[70:71], v[70:71] op_sel_hi:[0,1]
	v_pk_add_f32 v[120:121], v[120:121], v[122:123]
	v_pk_add_f32 v[64:65], v[64:65], v[68:69]
	v_mul_f32_e32 v124, v56, v56
	v_pk_add_f32 v[64:65], v[120:121], v[64:65]
	v_mul_f32_e32 v126, v57, v57
	v_mul_f32_e32 v66, v58, v58
	v_mul_f32_e32 v70, v59, v59
	v_add_f32_e32 v68, v64, v65
	v_pk_add_f32 v[64:65], v[124:125], v[126:127]
	v_pk_add_f32 v[66:67], v[66:67], v[70:71]
	s_cselect_b32 s50, s16, s48
	v_pk_add_f32 v[64:65], v[64:65], v[66:67]
	s_ashr_i32 s51, s50, 31
	v_add_f32_e32 v64, v64, v65
	ds_bpermute_b32 v65, v226, v68
	s_waitcnt lgkmcnt(0)
	v_add_f32_e32 v65, v68, v65
	ds_bpermute_b32 v66, v227, v65
	s_waitcnt lgkmcnt(0)
	v_add_f32_e32 v65, v65, v66
	ds_bpermute_b32 v66, v228, v65
	s_waitcnt lgkmcnt(0)
	v_add_f32_e32 v65, v65, v66
	ds_bpermute_b32 v66, v229, v65
	s_waitcnt lgkmcnt(0)
	v_add_f32_e32 v65, v65, v66
	ds_bpermute_b32 v66, v230, v65
	s_waitcnt lgkmcnt(0)
	v_add_f32_e32 v65, v65, v66
	ds_bpermute_b32 v66, v231, v65
	s_waitcnt lgkmcnt(0)
	v_add_f32_e32 v65, v65, v66
	v_fmamk_f32 v65, v65, 0x3a800000, v223
	v_cmp_gt_f32_e32 vcc, s64, v65
	v_mul_f32_e32 v66, 0x4f800000, v65
	s_nop 0
	v_cndmask_b32_e32 v65, v65, v66, vcc
	v_sqrt_f32_e32 v66, v65
	s_nop 0
	v_add_u32_e32 v67, -1, v66
	v_fma_f32 v68, -v67, v66, v65
	v_cmp_ge_f32_e64 s[38:39], 0, v68
	v_add_u32_e32 v68, 1, v66
	s_nop 0
	v_cndmask_b32_e64 v67, v66, v67, s[38:39]
	v_fma_f32 v66, -v68, v66, v65
	v_cmp_lt_f32_e64 s[38:39], 0, v66
	s_nop 1
	v_cndmask_b32_e64 v66, v67, v68, s[38:39]
	v_mul_f32_e32 v67, 0x37800000, v66
	v_cndmask_b32_e32 v66, v66, v67, vcc
	v_cmp_class_f32_e32 vcc, v65, v222
	s_nop 1
	v_cndmask_b32_e32 v65, v66, v65, vcc
	v_div_scale_f32 v66, s[0:1], v65, v65, 1.0
	v_rcp_f32_e32 v67, v66
	s_nop 0
	v_fma_f32 v68, -v66, v67, 1.0
	v_fmac_f32_e32 v67, v68, v67
	v_div_scale_f32 v68, vcc, 1.0, v65, 1.0
	v_mul_f32_e32 v69, v68, v67
	v_fma_f32 v70, -v66, v69, v68
	v_fmac_f32_e32 v69, v70, v67
	v_fma_f32 v66, -v66, v69, v68
	v_div_fmas_f32 v66, v66, v67, v69
	v_div_fixup_f32 v68, v66, v65, 1.0
	ds_bpermute_b32 v65, v226, v64
	s_waitcnt lgkmcnt(0)
	v_add_f32_e32 v64, v64, v65
	ds_bpermute_b32 v65, v227, v64
	s_waitcnt lgkmcnt(0)
	v_add_f32_e32 v64, v64, v65
	ds_bpermute_b32 v65, v228, v64
	s_waitcnt lgkmcnt(0)
	v_add_f32_e32 v64, v64, v65
	ds_bpermute_b32 v65, v229, v64
	s_waitcnt lgkmcnt(0)
	v_add_f32_e32 v64, v64, v65
	ds_bpermute_b32 v65, v230, v64
	s_waitcnt lgkmcnt(0)
	v_add_f32_e32 v64, v64, v65
	ds_bpermute_b32 v65, v231, v64
	s_waitcnt lgkmcnt(0)
	v_add_f32_e32 v64, v64, v65
	v_fmamk_f32 v64, v64, 0x3a800000, v223
	v_cmp_gt_f32_e32 vcc, s64, v64
	v_mul_f32_e32 v65, 0x4f800000, v64
	s_nop 0
	v_cndmask_b32_e32 v64, v64, v65, vcc
	v_sqrt_f32_e32 v65, v64
	s_nop 0
	v_add_u32_e32 v66, -1, v65
	v_fma_f32 v67, -v66, v65, v64
	v_cmp_ge_f32_e64 s[38:39], 0, v67
	v_add_u32_e32 v67, 1, v65
	s_nop 0
	v_cndmask_b32_e64 v66, v65, v66, s[38:39]
	v_fma_f32 v65, -v67, v65, v64
	v_cmp_lt_f32_e64 s[38:39], 0, v65
	s_nop 1
	v_cndmask_b32_e64 v65, v66, v67, s[38:39]
	v_mul_f32_e32 v66, 0x37800000, v65
	v_cndmask_b32_e32 v65, v65, v66, vcc
	v_cmp_class_f32_e32 vcc, v64, v222
	s_nop 1
	v_cndmask_b32_e32 v64, v65, v64, vcc
	v_div_scale_f32 v65, s[0:1], v64, v64, 1.0
	v_rcp_f32_e32 v66, v65
	s_lshl_b64 s[0:1], s[48:49], 11
	v_lshl_add_u64 v[122:123], v[84:85], 0, s[0:1]
	s_lshl_b64 s[0:1], s[50:51], 11
	v_fma_f32 v67, -v65, v66, 1.0
	v_fmac_f32_e32 v66, v67, v66
	v_div_scale_f32 v67, vcc, 1.0, v64, 1.0
	v_mul_f32_e32 v69, v67, v66
	v_fma_f32 v70, -v65, v69, v67
	v_fmac_f32_e32 v69, v70, v66
	v_fma_f32 v65, -v65, v69, v67
	v_div_fmas_f32 v65, v65, v66, v69
	v_div_fixup_f32 v120, v65, v64, 1.0
	ds_read_b128 v[64:67], v252
	v_pk_mul_f32 v[36:37], v[36:37], v[68:69] op_sel_hi:[1,0]
	v_pk_mul_f32 v[38:39], v[38:39], v[68:69] op_sel_hi:[1,0]
	v_lshl_add_u64 v[70:71], v[84:85], 0, s[0:1]
	v_mov_b32_e32 v121, v120
	s_andn2_b64 vcc, exec, s[22:23]
	s_waitcnt lgkmcnt(0)
	v_pk_mul_f32 v[38:39], v[66:67], v[38:39]
	v_pk_mul_f32 v[36:37], v[64:65], v[36:37]
	s_nop 0
	v_cvt_pk_bf16_f32 v36, v36, v37
	v_cvt_pk_bf16_f32 v37, v38, v39
	global_store_dwordx2 v[122:123], v[36:37], off
	v_cndmask_b32_e64 v36, 0, 1, s[22:23]
	v_cmp_ne_u32_e64 s[38:39], 1, v36
	s_cbranch_vccnz .LBB0_939
	v_mov_b32_e32 v36, v120
	v_mov_b32_e32 v37, v120
	v_pk_mul_f32 v[34:35], v[34:35], v[36:37]
	v_pk_mul_f32 v[32:33], v[32:33], v[120:121]
	v_pk_mul_f32 v[34:35], v[66:67], v[34:35]
	v_pk_mul_f32 v[32:33], v[64:65], v[32:33]
	s_nop 0
	v_cvt_pk_bf16_f32 v32, v32, v33
	v_cvt_pk_bf16_f32 v33, v34, v35
	global_store_dwordx2 v[70:71], v[32:33], off
; __device__ __forceinline__ unsigned pk2(float lo, float hi) { return pg8::cvt_pk_bf16(lo, hi); }
; __device__ __forceinline__ void row_phase(const bf16* m1, const float* g1, const bf16* m2, const float* g2, const float* xin, float* xout, const float* gpre, bf16* hout, int gw, int NGW, int lane_in) {
;     ...
;             v2u* ho0 = (v2u*)(hout + (size_t)row * DM) + lane; v2u* ho1 = (v2u*)(hout + (size_t)row2 * DM) + lane;
; #pragma unroll
;             for (int j = 0; j < 4; ++j) { const f32x4 g = ((const f32x4*)gpre)[64 * j + lane]; const f32x4 y0 = v[0][j] * r0 * g, y1 = v[1][j] * r1 * g;
;                 v2u a0, a1; a0.x = pk2(y0[0], y0[1]); a0.y = pk2(y0[2], y0[3]); a1.x = pk2(y1[0], y1[1]); a1.y = pk2(y1[2], y1[3]); ho0[64 * j] = a0; if (two) ho1[64 * j] = a1; }
;         }
; #pragma unroll
;         for (int j = 0; j < 4; ++j) { v[0][j] = nv[0][j]; v[1][j] = nv[1][j]; w[0][j] = nw[0][j]; w[1][j] = nw[1][j]; w2[0][j] = nw2[0][j]; w2[1][j] = nw2[1][j]; }
;     }
.LBB0_939:
	ds_read_b128 v[32:35], v252 offset:1024
	v_mov_b32_e32 v69, v68
	v_mov_b32_e32 v36, v68
	v_mov_b32_e32 v37, v68
	v_pk_mul_f32 v[38:39], v[46:47], v[36:37]
	v_pk_mul_f32 v[44:45], v[44:45], v[68:69]
	s_and_b64 vcc, exec, s[38:39]
	s_waitcnt lgkmcnt(0)
	v_pk_mul_f32 v[38:39], v[38:39], v[34:35]
	v_pk_mul_f32 v[44:45], v[44:45], v[32:33]
	s_nop 0
	v_cvt_pk_bf16_f32 v44, v44, v45
	v_cvt_pk_bf16_f32 v45, v38, v39
	global_store_dwordx2 v[122:123], v[44:45], off offset:512
	s_cbranch_vccnz .LBB0_941
	v_mov_b32_e32 v38, v120
	v_mov_b32_e32 v39, v120
	v_pk_mul_f32 v[38:39], v[42:43], v[38:39]
	v_pk_mul_f32 v[40:41], v[40:41], v[120:121]
	v_pk_mul_f32 v[34:35], v[38:39], v[34:35]
	v_pk_mul_f32 v[32:33], v[40:41], v[32:33]
	s_nop 0
	v_cvt_pk_bf16_f32 v32, v32, v33
	v_cvt_pk_bf16_f32 v33, v34, v35
	global_store_dwordx2 v[70:71], v[32:33], off offset:512
.LBB0_941:
	ds_read_b128 v[32:35], v252 offset:2048
	v_pk_mul_f32 v[36:37], v[54:55], v[36:37]
	v_pk_mul_f32 v[38:39], v[52:53], v[68:69]
	s_and_b64 vcc, exec, s[38:39]
	s_waitcnt lgkmcnt(0)
	v_pk_mul_f32 v[36:37], v[36:37], v[34:35]
	v_pk_mul_f32 v[38:39], v[38:39], v[32:33]
	s_nop 0
	v_cvt_pk_bf16_f32 v38, v38, v39
	v_cvt_pk_bf16_f32 v39, v36, v37
	global_store_dwordx2 v[122:123], v[38:39], off offset:1024
	s_cbranch_vccnz .LBB0_943
	v_mov_b32_e32 v36, v120
	v_mov_b32_e32 v37, v120
	v_pk_mul_f32 v[36:37], v[50:51], v[36:37]
	v_pk_mul_f32 v[38:39], v[48:49], v[120:121]
	v_pk_mul_f32 v[34:35], v[36:37], v[34:35]
	v_pk_mul_f32 v[32:33], v[38:39], v[32:33]
	s_nop 0
	v_cvt_pk_bf16_f32 v32, v32, v33
	v_cvt_pk_bf16_f32 v33, v34, v35
	global_store_dwordx2 v[70:71], v[32:33], off offset:1024
.LBB0_943:
	ds_read_b128 v[32:35], v252 offset:3072
	v_mov_b32_e32 v36, v68
	v_mov_b32_e32 v37, v68
	v_pk_mul_f32 v[38:39], v[60:61], v[68:69]
	v_pk_mul_f32 v[36:37], v[62:63], v[36:37]
	s_and_b64 vcc, exec, s[38:39]
	s_waitcnt lgkmcnt(0)
	v_pk_mul_f32 v[36:37], v[36:37], v[34:35]
	v_pk_mul_f32 v[38:39], v[38:39], v[32:33]
	s_nop 0
	v_cvt_pk_bf16_f32 v38, v38, v39
	v_cvt_pk_bf16_f32 v39, v36, v37
	global_store_dwordx2 v[122:123], v[38:39], off offset:1536
	s_cbranch_vccnz .LBB0_928
	v_mov_b32_e32 v36, v120
	v_mov_b32_e32 v37, v120
	v_pk_mul_f32 v[36:37], v[58:59], v[36:37]
	v_pk_mul_f32 v[38:39], v[56:57], v[120:121]
	v_pk_mul_f32 v[34:35], v[36:37], v[34:35]
	v_pk_mul_f32 v[32:33], v[38:39], v[32:33]
	s_nop 0
	v_cvt_pk_bf16_f32 v32, v32, v33
	v_cvt_pk_bf16_f32 v33, v34, v35
	global_store_dwordx2 v[70:71], v[32:33], off offset:1536
	s_branch .LBB0_928
